# GEMM mode-2 (gated branch merge) epilogue de-serialised: 4 batches of 8 loads in flight instead of 27 dependent round trips; A loop scale folded into a_q weight columns + (bias-m) into QK accumulator
# speedup vs baseline: 1.0479x; 1.0207x over previous
; #define LAS __attribute__((address_space(3)))
;     DI unsigned char* ws() const { return (unsigned char*)gp(35); }
; DI void xcd_post(unsigned* bar) { if (threadIdx.x == 0) (void)xb_add(&bar[XB_XCNT(xb_xcc_id())], 1u); }
; __global__ __launch_bounds__(NTHR, 2) void mega(KArgs A, int ph_lo, int ph_hi) {
;     ...
;     Params P; P.t = (LAS const unsigned long long*)(shm + PTAB_OFF);
;     volatile LAS unsigned* xst = (volatile LAS unsigned*)(shm + PTAB_OFF + 384);
;     const int wave_s = __builtin_amdgcn_readfirstlane((int)(threadIdx.x >> 6));
;     int nbar = 0;
;     for (int ph = ph_lo; ph < ph_hi; ++ph) {
;         if (ph > 0 && (((ph - 1) % 16) == 4 || ((ph - 1) % 16) == 5)) continue;
;         const int nrep = (REP_MASK != 0 && ph > 0 && ((REP_MASK >> ((ph - 1) % 16)) & 1)) ? 2 : 1;
;         for (int rep = 0; rep < nrep; ++rep) {
;             if (ph > ph_lo || rep > 0) { unsigned* xbw = (unsigned*)(P.ws() + WS_XB); if (nbar == 0) { grid.sync(); xcd_post(xbw); } else xcd_barrier(xbw, xst); ++nbar; }
;             { int l_; asm volatile("v_mbcnt_lo_u32_b32 %0, -1, 0\n\tv_mbcnt_hi_u32_b32 %0, -1, %0" : "=v"(l_)); P.tid = wave_s * 64 + l_; }
;             run_phase(P, ph, shm, rep);
.LBB0_290:
	s_or_b64 exec, exec, s[4:5]
	s_load_dwordx2 s[40:41], s[0:1], 0x120
	v_readfirstlane_b32 s0, v1
	s_waitcnt lgkmcnt(0)
	s_barrier
	s_cmp_ge_i32 s40, s41
	s_cbranch_scc1 .LBB0_835
	s_andn2_b32 s0, s0, 63
	v_lshrrev_b32_e32 v2, 20, v0
	v_lshrrev_b32_e32 v0, 10, v0
	v_writelane_b32 v242, s0, 2
	v_or_b32_e32 v0, v0, v2
	s_movk_i32 s0, 0x3ff
	s_cmp_eq_u32 s2, 0
	v_and_or_b32 v0, v0, s0, v1
	s_cselect_b64 s[0:1], -1, 0
	v_writelane_b32 v242, s0, 3
	s_mov_b32 s20, s40
	s_lshl_b32 s72, s3, 9
	v_writelane_b32 v242, s1, 4
	s_lshl_b32 s0, s2, 9
	v_writelane_b32 v242, s0, 5
	s_lshl_b32 s0, s2, 3
	v_writelane_b32 v242, s0, 6
	s_add_i32 s0, 0, 0x25380
	v_writelane_b32 v242, s0, 7
	s_add_i32 s0, 0, 0x25384
	v_writelane_b32 v242, s0, 8
	s_add_i32 s0, 0, 0x25240
	v_writelane_b32 v242, s0, 9
	s_add_i32 s0, 0, 0x25250
	v_writelane_b32 v242, s0, 10
	s_add_i32 s0, 0, 0x25228
	v_writelane_b32 v242, s0, 11
	s_add_i32 s0, 0, 0x252c8
	v_writelane_b32 v242, s0, 12
	s_add_i32 s0, 0, 0x25218
	v_writelane_b32 v242, s0, 13
	s_add_i32 s0, 0, 0x25210
	v_writelane_b32 v242, s0, 14
	s_add_i32 s0, 0, 0x25268
	v_writelane_b32 v242, s0, 15
	s_add_i32 s0, 0, 0x25278
	v_writelane_b32 v242, s0, 16
	s_add_i32 s0, 0, 0x15000
	v_writelane_b32 v242, s0, 17
	s_add_i32 s0, 0, 0x25260
	v_writelane_b32 v242, s0, 18
	s_add_i32 s0, 0, 0x25220
	v_writelane_b32 v242, s0, 19
	s_mov_b32 s0, 0
	v_writelane_b32 v242, s0, 20
	v_cmp_eq_u32_e64 s[0:1], 0, v0
	s_lshl_b32 s74, s3, 4
	s_lshl_b32 s75, s2, 6
	v_writelane_b32 v242, s0, 21
	s_mul_i32 s76, s3, 0x5c000
	s_mul_hi_i32 s77, s74, 0x5c00
	v_writelane_b32 v242, s1, 22
	v_writelane_b32 v242, s40, 23
	s_add_i32 s80, 0, 0x25208
	s_mov_b32 s21, 0
	v_writelane_b32 v242, s41, 24
	v_writelane_b32 v242, s72, 25
	v_writelane_b32 v242, s74, 26
	v_writelane_b32 v242, s75, 27
	v_writelane_b32 v242, s76, 28
	s_lshl_b32 s87, s3, 3
	s_lshl_b32 s91, s3, 6
	v_writelane_b32 v242, s77, 29
	s_movk_i32 s92, 0x5c00
	s_add_i32 s86, 0, 0x25318
	v_mov_b32_e32 v1, 0
	v_mov_b32_e32 v180, 0x1000
	v_mov_b32_e32 v181, 0x2000
	v_mov_b32_e32 v182, 0x29303000
	v_mov_b32_e32 v183, 1
	s_movk_i32 s48, 0x1ff
	v_mov_b32_e32 v184, 0x29300000
	s_movk_i32 s78, 0x1000
	s_movk_i32 s79, 0x1fff
	v_mov_b32_e32 v185, 0x358637bd
	s_mov_b32 s95, 0x800000
	s_add_i32 s81, 0, 0x25310
	s_movk_i32 s82, 0x3fff
	s_movk_i32 s30, 0xff00
	s_movk_i32 s31, 0x80
	s_movk_i32 s23, 0x1800
	s_movk_i32 s45, 0x2000
	s_movk_i32 s13, 0x60
	s_add_i32 s88, 0, 0x14c10
	s_movk_i32 s18, 0x5b
	s_add_i32 s19, 0, 0x14800
	s_movk_i32 s34, 0x70
	s_mov_b32 s97, 0x4138aa3b
	v_mov_b32_e32 v186, 0xffffe000
	v_mov_b32_e32 v187, 0xfffff000
	v_mov_b32_e32 v188, 0x3f24fd5c
	v_mov_b32_e32 v189, 0x3f4ccccd
	v_mov_b32_e32 v190, 0x5c00
	v_mov_b32_e32 v191, 0x100
	v_mov_b32_e32 v192, 0x400
	s_mov_b64 s[26:27], 0x800
	s_mov_b64 s[38:39], 0x80
	s_mov_b64 s[42:43], 0x2a80
	s_mov_b32 s44, 1.0
	v_writelane_b32 v242, s80, 30
	v_writelane_b32 v242, s81, 31
	s_branch .LBB0_294

; DI unsigned cvtpk(float lo, float hi) { unsigned r; asm volatile("v_cvt_pk_bf16_f32 %0, %1, %2" : "=v"(r) : "v"(lo), "v"(hi)); return r; }
; DI void cvt_job(const float* __restrict__ src, int K, int N, int Npad, bf16_t* __restrict__ dst, int mode, float* tile, const int tid) {
;     ...
;         f32x4 v[8];
; #pragma unroll
;         for (int i = 0; i < 8; ++i) { v[i] = (f32x4){0.f, 0.f, 0.f, 0.f};
;             if (n0 + c < N) v[i] = *(const f32x4*)(src + (size_t)(k0 + r + 8 * i) * N + n0 + c); }
;         __syncthreads();
; #pragma unroll
;         for (int i = 0; i < 8; ++i) { float* tp = tile + u0 * 4160 + (r + 8 * i) * 65 + cc; tp[0] = v[i][0]; tp[1] = v[i][1]; tp[2] = v[i][2]; tp[3] = v[i][3]; }
;         __syncthreads();
; #pragma unroll
;         for (int u = 0; u < 4; ++u) {
;             float x[8];
; #pragma unroll
;             for (int j = 0; j < 8; ++j) x[j] = tile[u * 4160 + (kc + j) * 65 + wn];
;             const int n = n0 + u * 64 + wn; const int drow = mode == 0 ? n : ((n >> 7) * 256 + (mode == 2 ? 128 : 0) + (n & 127));
;             u32x4 w; w.x = cvtpk(x[0], x[1]); w.y = cvtpk(x[2], x[3]); w.z = cvtpk(x[4], x[5]); w.w = cvtpk(x[6], x[7]);
;             *(u32x4*)(dst + (size_t)drow * K + k0 + kc) = w;
;         }
.LBB0_498:
	s_or_b64 exec, exec, s[58:59]
	s_barrier
	s_waitcnt vmcnt(0)
	s_cmp_eq_u32 s20, 0
	s_cselect_b32 s32, 0x3e38aa3b, 1.0
	s_cmp_lt_u32 s56, 0x400
	s_cselect_b32 s32, s32, 1.0
	s_cmp_eq_u32 s32, 1.0
	s_cbranch_scc1 .Lcvt_noscale
	v_mul_f32_e32 v2, s32, v2
	v_mul_f32_e32 v3, s32, v3
	v_mul_f32_e32 v4, s32, v4
	v_mul_f32_e32 v5, s32, v5
	v_mul_f32_e32 v6, s32, v6
	v_mul_f32_e32 v7, s32, v7
	v_mul_f32_e32 v8, s32, v8
	v_mul_f32_e32 v9, s32, v9
	v_mul_f32_e32 v10, s32, v10
	v_mul_f32_e32 v11, s32, v11
	v_mul_f32_e32 v12, s32, v12
	v_mul_f32_e32 v13, s32, v13
	v_mul_f32_e32 v14, s32, v14
	v_mul_f32_e32 v15, s32, v15
	v_mul_f32_e32 v16, s32, v16
	v_mul_f32_e32 v17, s32, v17
	v_mul_f32_e32 v18, s32, v18
	v_mul_f32_e32 v19, s32, v19
	v_mul_f32_e32 v20, s32, v20
	v_mul_f32_e32 v21, s32, v21
	v_mul_f32_e32 v22, s32, v22
	v_mul_f32_e32 v23, s32, v23
	v_mul_f32_e32 v24, s32, v24
	v_mul_f32_e32 v25, s32, v25
	v_mul_f32_e32 v26, s32, v26
	v_mul_f32_e32 v27, s32, v27
	v_mul_f32_e32 v28, s32, v28
	v_mul_f32_e32 v29, s32, v29
	v_mul_f32_e32 v30, s32, v30
	v_mul_f32_e32 v31, s32, v31
	v_mul_f32_e32 v32, s32, v32
	v_mul_f32_e32 v33, s32, v33
.Lcvt_noscale:
	ds_write2_b32 v46, v6, v7 offset1:1
	ds_write2_b32 v46, v8, v9 offset0:2 offset1:3
	v_add_u32_e32 v6, 0x820, v46
	ds_write2_b32 v6, v2, v3 offset1:1
	v_add_u32_e32 v2, 0x828, v46
	ds_write2_b32 v2, v4, v5 offset1:1
	v_add_u32_e32 v2, 0x1040, v46
	ds_write2_b32 v2, v14, v15 offset1:1
	v_add_u32_e32 v2, 0x1048, v46
	ds_write2_b32 v2, v16, v17 offset1:1
	v_add_u32_e32 v2, 0x1860, v46
	ds_write2_b32 v2, v10, v11 offset1:1
	v_add_u32_e32 v2, 0x1868, v46
	ds_write2_b32 v2, v12, v13 offset1:1
	v_add_u32_e32 v2, 0x2080, v46
	ds_write2_b32 v2, v22, v23 offset1:1
	v_add_u32_e32 v2, 0x2088, v46
	ds_write2_b32 v2, v24, v25 offset1:1
	v_add_u32_e32 v2, 0x28a0, v46
	ds_write2_b32 v2, v18, v19 offset1:1
	v_add_u32_e32 v2, 0x28a8, v46
	ds_write2_b32 v2, v20, v21 offset1:1
	v_add_u32_e32 v2, 0x30c0, v46
	ds_write2_b32 v2, v30, v31 offset1:1
	v_add_u32_e32 v2, 0x30c8, v46
	ds_write2_b32 v2, v32, v33 offset1:1
	v_add_u32_e32 v2, 0x38e0, v46
	ds_write2_b32 v2, v26, v27 offset1:1
	v_add_u32_e32 v2, 0x38e8, v46
	v_add_u32_e32 v12, s56, v44
	ds_write2_b32 v2, v28, v29 offset1:1
	v_lshlrev_b32_e32 v2, 1, v12
	s_waitcnt lgkmcnt(0)
	s_barrier
	v_and_or_b32 v13, v2, s30, v0
	ds_read2_b32 v[2:3], v47 offset1:65
	ds_read2_b32 v[4:5], v47 offset0:130 offset1:195
	v_add_u32_e32 v10, 0x400, v47
	ds_read2_b32 v[8:9], v10 offset0:4 offset1:69
	ds_read2_b32 v[10:11], v10 offset0:134 offset1:199
	v_cndmask_b32_e64 v13, v13, v12, s[6:7]
	s_waitcnt lgkmcnt(3)
	v_cvt_pk_bf16_f32 v2, v2, v3
	s_waitcnt lgkmcnt(2)
	v_cvt_pk_bf16_f32 v3, v4, v5
	s_waitcnt lgkmcnt(1)
	v_cvt_pk_bf16_f32 v4, v8, v9
	v_mad_u64_u32 v[8:9], s[36:37], v13, s14, 0
	s_waitcnt lgkmcnt(0)
	v_cvt_pk_bf16_f32 v5, v10, v11
	v_ashrrev_i32_e32 v11, 31, v13
	v_mov_b32_e32 v10, v9
	s_ashr_i32 s55, s54, 31
	v_mad_u64_u32 v[10:11], s[36:37], v11, s14, v[10:11]
	v_lshl_add_u64 v[6:7], s[54:55], 1, v[40:41]
	v_mov_b32_e32 v9, v10
	v_lshl_add_u64 v[8:9], v[8:9], 1, v[6:7]
	v_add_u32_e32 v13, 64, v12
	global_store_dwordx4 v[8:9], v[2:5], off
	v_add_u32_e32 v8, 0x4400, v47
	ds_read2_b32 v[8:9], v8 offset0:68 offset1:133
	v_lshlrev_b32_e32 v2, 1, v13
	v_and_b32_e32 v2, 0xffffff00, v2
	v_and_b32_e32 v3, 0x7f, v13
	v_or3_b32 v14, v3, v2, s15
	v_add_u32_e32 v2, 0x4000, v47
	v_add_u32_e32 v4, 0x4200, v47
	ds_read2_b32 v[2:3], v2 offset0:64 offset1:129
	ds_read2_b32 v[4:5], v4 offset0:66 offset1:131
	v_add_u32_e32 v10, 0x4600, v47
	v_cndmask_b32_e64 v13, v14, v13, s[6:7]
	ds_read2_b32 v[10:11], v10 offset0:70 offset1:135
	s_waitcnt lgkmcnt(2)
	v_cvt_pk_bf16_f32 v2, v2, v3
	s_waitcnt lgkmcnt(1)
	v_cvt_pk_bf16_f32 v3, v4, v5
	v_cvt_pk_bf16_f32 v4, v8, v9
	v_mad_u64_u32 v[8:9], s[36:37], v13, s14, 0
	s_waitcnt lgkmcnt(0)
	v_cvt_pk_bf16_f32 v5, v10, v11
	v_ashrrev_i32_e32 v11, 31, v13
	v_mov_b32_e32 v10, v9
	v_mad_u64_u32 v[10:11], s[36:37], v11, s14, v[10:11]
	v_mov_b32_e32 v9, v10
	v_lshl_add_u64 v[8:9], v[8:9], 1, v[6:7]
	v_add_u32_e32 v13, 0x80, v12
	global_store_dwordx4 v[8:9], v[2:5], off
	v_add_u32_e32 v8, 0x8400, v47
	v_add_u32_e32 v10, 0x8800, v47
	v_lshlrev_b32_e32 v2, 1, v13
	v_and_or_b32 v14, v2, s30, v0
	v_add_u32_e32 v2, 0x8000, v47
	ds_read2_b32 v[2:3], v2 offset0:128 offset1:193
	ds_read2_b32 v[4:5], v8 offset0:2 offset1:67
	ds_read2_b32 v[8:9], v8 offset0:132 offset1:197
	v_cndmask_b32_e64 v13, v14, v13, s[6:7]
	ds_read2_b32 v[10:11], v10 offset0:6 offset1:71
	s_waitcnt lgkmcnt(3)
	v_cvt_pk_bf16_f32 v2, v2, v3
	s_waitcnt lgkmcnt(2)
	v_cvt_pk_bf16_f32 v3, v4, v5
	s_waitcnt lgkmcnt(1)
	v_cvt_pk_bf16_f32 v4, v8, v9
	v_mad_u64_u32 v[8:9], s[36:37], v13, s14, 0
	s_waitcnt lgkmcnt(0)
	v_cvt_pk_bf16_f32 v5, v10, v11
	v_ashrrev_i32_e32 v11, 31, v13
	v_mov_b32_e32 v10, v9
	v_mad_u64_u32 v[10:11], s[36:37], v11, s14, v[10:11]
	v_mov_b32_e32 v9, v10
	v_lshl_add_u64 v[8:9], v[8:9], 1, v[6:7]
	v_add_u32_e32 v12, 0xc0, v12
	global_store_dwordx4 v[8:9], v[2:5], off
	v_add_u32_e32 v8, 0xc600, v47
	ds_read2_b32 v[8:9], v8 offset0:68 offset1:133
	v_lshlrev_b32_e32 v2, 1, v12
	v_and_b32_e32 v2, 0xffffff00, v2
	v_and_b32_e32 v3, 0x7f, v12
	v_or3_b32 v13, v3, v2, s15
	v_add_u32_e32 v2, 0xc200, v47
	v_add_u32_e32 v4, 0xc400, v47
	ds_read2_b32 v[2:3], v2 offset0:64 offset1:129
	ds_read2_b32 v[4:5], v4 offset0:66 offset1:131
	v_add_u32_e32 v10, 0xc800, v47
	v_cndmask_b32_e64 v12, v13, v12, s[6:7]
	ds_read2_b32 v[10:11], v10 offset0:70 offset1:135
	s_waitcnt lgkmcnt(2)
	v_cvt_pk_bf16_f32 v2, v2, v3
	s_waitcnt lgkmcnt(1)
	v_cvt_pk_bf16_f32 v3, v4, v5
	v_cvt_pk_bf16_f32 v4, v8, v9
	v_mad_u64_u32 v[8:9], s[36:37], v12, s14, 0
	s_waitcnt lgkmcnt(0)
	v_cvt_pk_bf16_f32 v5, v10, v11
	v_ashrrev_i32_e32 v11, 31, v12
	v_mov_b32_e32 v10, v9
	v_mad_u64_u32 v[10:11], s[36:37], v11, s14, v[10:11]
	v_mov_b32_e32 v9, v10
	s_add_i32 s28, s28, s3
	s_add_i32 s25, s25, s91
	v_lshl_add_u64 v[6:7], v[8:9], 1, v[6:7]
	s_cmp_lt_i32 s28, s17
	global_store_dwordx4 v[6:7], v[2:5], off
	s_cbranch_scc0 .LBB0_451

; #define PG8_STAGE(bufoff, gbase, voff) do { _Pragma("unroll") for (int _i = 0; _i < 2; ++_i) \
;         __builtin_amdgcn_global_load_lds((const unsigned*)((const char*)(gbase) + (voff)[_i]), (LAS unsigned*)(lds + (bufoff) + ldsw + _i * 8192), 16, 0, 0); } while (0)
; #define PG8_LDA(dst, b, h) do { _Pragma("unroll") for (int m = 0; m < 4; ++m) _Pragma("unroll") for (int k = 0; k < 2; ++k) dst[m][k] = *(const LAS bf16x8*)(lds + PG8_SA(b, h) + aoff + m * 2048 + k * 1024); } while (0)
; #define PG8_WAIT_V(n) asm volatile("s_waitcnt vmcnt(" #n ")" ::: "memory")
; #define PG8_WAIT_L(n) asm volatile("s_waitcnt lgkmcnt(" #n ")" ::: "memory")
; template <class Epi>
; DI void gemm_phase(LAS unsigned char* lds, const Gemm g, const Order& S, const Epi& E, const int tid) {
;     ...
;         for (int t = 0; t < nt; t += 2) {
;             const bool last = (t == nt - 2);
;             const char* a1 = cA + (size_t)(t + 1) * kstep;
;             const char* a2 = last ? nA : cA + (size_t)(t + 2) * kstep; const char* b2 = last ? nB : cB + (size_t)(t + 2) * kstep;
;             const char* a3 = a2 + kstep; const char* b3 = b2 + kstep;
;             PG8_LDB(B0, 0, 0); PG8_SCHED; PG8_LDA(At, 0, 0); PG8_STAGE(PG8_SA(1, 1), a1 + hstepA, voffA);
;             PG8_WAIT_L(8); PG8_BAR; PG8_WAIT_L(0); PG8_MMA(0, 0, At, B0); PG8_BAR; PG8_SCHED;
;             PG8_LDB(B1, 0, 1); PG8_STAGE(PG8_SB(0, 0), b2, voffB);
;             PG8_BAR; PG8_WAIT_L(0); PG8_MMA(0, 1, At, B1); PG8_BAR;
;             PG8_LDA(At, 0, 1); PG8_STAGE(PG8_SA(0, 0), a2, voffA);
;             PG8_BAR; PG8_WAIT_L(0); PG8_MMA(1, 0, At, B0); PG8_BAR; PG8_SCHED;
;             PG8_STAGE(PG8_SB(0, 1), b2 + hstepB, voffB);
;             PG8_WAIT_V(6); PG8_BAR; PG8_MMA(1, 1, At, B1); PG8_BAR;
;             PG8_LDB(B0, 1, 0); PG8_SCHED; PG8_LDA(At, 1, 0); PG8_STAGE(PG8_SA(0, 1), a2 + hstepA, voffA);
;             PG8_WAIT_L(8); PG8_BAR; PG8_WAIT_L(0); PG8_MMA(0, 0, At, B0); PG8_BAR; PG8_SCHED;
;             PG8_LDB(B1, 1, 1); PG8_STAGE(PG8_SB(1, 0), b3, voffB);
;             PG8_BAR; PG8_WAIT_L(0); PG8_MMA(0, 1, At, B1); PG8_BAR;
;             PG8_LDA(At, 1, 1); PG8_STAGE(PG8_SA(1, 0), a3, voffA);
;             PG8_BAR; PG8_WAIT_L(0); PG8_MMA(1, 0, At, B0); PG8_BAR; PG8_SCHED;
;             PG8_STAGE(PG8_SB(1, 1), b3 + hstepB, voffB);
;             PG8_WAIT_V(6); PG8_BAR; PG8_MMA(1, 1, At, B1); PG8_BAR;
.LBB0_629:
	s_add_i32 vcc_hi, s76, 2
	s_add_u32 s78, s0, 0x80
	s_addc_u32 s77, s1, 0
	s_add_i32 s46, 0, 0x10000
	v_add_u32_e32 v152, s46, v157
	ds_read_b128 v[140:143], v152
	ds_read_b128 v[144:147], v152 offset:1024
	ds_read_b128 v[148:151], v152 offset:2048
	ds_read_b128 v[152:155], v152 offset:3072
	s_cmp_eq_u32 s98, s76
	s_cselect_b32 s76, s74, s78
	s_cselect_b32 s77, s75, s77
	s_cselect_b32 s79, s9, vcc_lo
	s_cselect_b32 s78, s8, s17
	v_lshl_add_u64 v[206:207], s[0:1], 0, v[138:139]
	s_add_i32 m0, s37, 0xc000
	ds_read_b128 v[160:163], v159
	ds_read_b128 v[164:167], v159 offset:1024
	ds_read_b128 v[168:171], v159 offset:2048
	ds_read_b128 v[172:175], v159 offset:3072
	ds_read_b128 v[176:179], v159 offset:4096
	ds_read_b128 v[194:197], v159 offset:5120
	ds_read_b128 v[198:201], v159 offset:6144
	ds_read_b128 v[202:205], v159 offset:7168
	global_load_lds_dwordx4 v[206:207], off
	v_lshl_add_u64 v[206:207], s[0:1], 0, v[136:137]
	s_add_i32 m0, s37, 0xe000
	s_nop 0
	global_load_lds_dwordx4 v[206:207], off
	s_waitcnt lgkmcnt(8)
	s_barrier
	s_waitcnt lgkmcnt(0)
	s_setprio 1
	s_waitcnt lgkmcnt(0)
	v_mfma_f32_16x16x32_bf16 v[126:129], v[140:143], v[160:163], v[126:129]
	v_mfma_f32_16x16x32_bf16 v[122:125], v[148:151], v[160:163], v[122:125]
	v_mfma_f32_16x16x32_bf16 v[110:113], v[140:143], v[168:171], v[110:113]
	v_mfma_f32_16x16x32_bf16 v[106:109], v[148:151], v[168:171], v[106:109]
	v_mfma_f32_16x16x32_bf16 v[94:97], v[140:143], v[176:179], v[94:97]
	v_mfma_f32_16x16x32_bf16 v[90:93], v[148:151], v[176:179], v[90:93]
	v_mfma_f32_16x16x32_bf16 v[78:81], v[140:143], v[198:201], v[78:81]
	v_mfma_f32_16x16x32_bf16 v[74:77], v[148:151], v[198:201], v[74:77]
	v_mfma_f32_16x16x32_bf16 v[126:129], v[144:147], v[164:167], v[126:129]
	v_mfma_f32_16x16x32_bf16 v[122:125], v[152:155], v[164:167], v[122:125]
	v_mfma_f32_16x16x32_bf16 v[110:113], v[144:147], v[172:175], v[110:113]
	v_mfma_f32_16x16x32_bf16 v[106:109], v[152:155], v[172:175], v[106:109]
	v_mfma_f32_16x16x32_bf16 v[94:97], v[144:147], v[194:197], v[94:97]
	v_mfma_f32_16x16x32_bf16 v[90:93], v[152:155], v[194:197], v[90:93]
	v_mfma_f32_16x16x32_bf16 v[78:81], v[144:147], v[202:205], v[78:81]
	v_mfma_f32_16x16x32_bf16 v[74:77], v[152:155], v[202:205], v[74:77]
	s_setprio 0
	s_barrier
	s_add_i32 s93, 0, 0x14000
	s_add_i32 s46, s46, s49
	v_add_u32_e32 v218, s93, v157
	v_lshl_add_u64 v[222:223], s[78:79], 0, v[0:1]
	s_mov_b32 m0, s46
	ds_read_b128 v[206:209], v218
	ds_read_b128 v[210:213], v218 offset:1024
	ds_read_b128 v[214:217], v218 offset:2048
	ds_read_b128 v[218:221], v218 offset:3072
	global_load_lds_dwordx4 v[222:223], off
	v_lshl_add_u64 v[224:225], s[78:79], 0, v[134:135]
	s_add_i32 m0, s46, 0x2000
	s_nop 0
	global_load_lds_dwordx4 v[224:225], off
	s_barrier
	s_waitcnt lgkmcnt(0)
	s_setprio 1
	s_waitcnt lgkmcnt(0)
	v_mfma_f32_16x16x32_bf16 v[118:121], v[206:209], v[160:163], v[118:121]
	v_mfma_f32_16x16x32_bf16 v[114:117], v[214:217], v[160:163], v[114:117]
	v_mfma_f32_16x16x32_bf16 v[102:105], v[206:209], v[168:171], v[102:105]
	v_mfma_f32_16x16x32_bf16 v[98:101], v[214:217], v[168:171], v[98:101]
	v_mfma_f32_16x16x32_bf16 v[86:89], v[206:209], v[176:179], v[86:89]
	v_mfma_f32_16x16x32_bf16 v[82:85], v[214:217], v[176:179], v[82:85]
	v_mfma_f32_16x16x32_bf16 v[70:73], v[206:209], v[198:201], v[70:73]
	v_mfma_f32_16x16x32_bf16 v[66:69], v[214:217], v[198:201], v[66:69]
	v_mfma_f32_16x16x32_bf16 v[118:121], v[210:213], v[164:167], v[118:121]
	v_mfma_f32_16x16x32_bf16 v[114:117], v[218:221], v[164:167], v[114:117]
	v_mfma_f32_16x16x32_bf16 v[102:105], v[210:213], v[172:175], v[102:105]
	v_mfma_f32_16x16x32_bf16 v[98:101], v[218:221], v[172:175], v[98:101]
	v_mfma_f32_16x16x32_bf16 v[86:89], v[210:213], v[194:197], v[86:89]
	v_mfma_f32_16x16x32_bf16 v[82:85], v[218:221], v[194:197], v[82:85]
	v_mfma_f32_16x16x32_bf16 v[70:73], v[210:213], v[202:205], v[70:73]
	v_mfma_f32_16x16x32_bf16 v[66:69], v[218:221], v[202:205], v[66:69]
	s_setprio 0
	s_mov_b32 m0, s37
	v_lshl_add_u64 v[226:227], s[76:77], 0, v[130:131]
	s_barrier
	ds_read_b128 v[160:163], v159 offset:16384
	ds_read_b128 v[164:167], v159 offset:17408
	ds_read_b128 v[168:171], v159 offset:18432
	ds_read_b128 v[172:175], v159 offset:19456
	ds_read_b128 v[176:179], v159 offset:20480
	ds_read_b128 v[194:197], v159 offset:21504
	ds_read_b128 v[198:201], v159 offset:22528
	ds_read_b128 v[202:205], v159 offset:23552
	global_load_lds_dwordx4 v[226:227], off
	v_lshl_add_u64 v[228:229], s[76:77], 0, v[132:133]
	s_mov_b32 m0, s14
	s_nop 0
	global_load_lds_dwordx4 v[228:229], off
	s_barrier
	s_waitcnt lgkmcnt(0)
	s_setprio 1
	s_waitcnt lgkmcnt(0)
	v_mfma_f32_16x16x32_bf16 v[62:65], v[140:143], v[160:163], v[62:65]
	v_mfma_f32_16x16x32_bf16 v[58:61], v[148:151], v[160:163], v[58:61]
	v_mfma_f32_16x16x32_bf16 v[46:49], v[140:143], v[168:171], v[46:49]
	v_mfma_f32_16x16x32_bf16 v[42:45], v[148:151], v[168:171], v[42:45]
	v_mfma_f32_16x16x32_bf16 v[30:33], v[140:143], v[176:179], v[30:33]
	v_mfma_f32_16x16x32_bf16 v[26:29], v[148:151], v[176:179], v[26:29]
	v_mfma_f32_16x16x32_bf16 v[14:17], v[140:143], v[198:201], v[14:17]
	v_mfma_f32_16x16x32_bf16 v[10:13], v[148:151], v[198:201], v[10:13]
	v_mfma_f32_16x16x32_bf16 v[62:65], v[144:147], v[164:167], v[62:65]
	v_mfma_f32_16x16x32_bf16 v[58:61], v[152:155], v[164:167], v[58:61]
	v_mfma_f32_16x16x32_bf16 v[46:49], v[144:147], v[172:175], v[46:49]
	v_mfma_f32_16x16x32_bf16 v[42:45], v[152:155], v[172:175], v[42:45]
	v_mfma_f32_16x16x32_bf16 v[30:33], v[144:147], v[194:197], v[30:33]
	v_mfma_f32_16x16x32_bf16 v[26:29], v[152:155], v[194:197], v[26:29]
	v_mfma_f32_16x16x32_bf16 v[14:17], v[144:147], v[202:205], v[14:17]
	v_mfma_f32_16x16x32_bf16 v[10:13], v[152:155], v[202:205], v[10:13]
	s_setprio 0
	s_barrier
; #define PG8_STAGE(bufoff, gbase, voff) do { _Pragma("unroll") for (int _i = 0; _i < 2; ++_i) \
;         __builtin_amdgcn_global_load_lds((const unsigned*)((const char*)(gbase) + (voff)[_i]), (LAS unsigned*)(lds + (bufoff) + ldsw + _i * 8192), 16, 0, 0); } while (0)
; #define PG8_LDA(dst, b, h) do { _Pragma("unroll") for (int m = 0; m < 4; ++m) _Pragma("unroll") for (int k = 0; k < 2; ++k) dst[m][k] = *(const LAS bf16x8*)(lds + PG8_SA(b, h) + aoff + m * 2048 + k * 1024); } while (0)
; #define PG8_WAIT_V(n) asm volatile("s_waitcnt vmcnt(" #n ")" ::: "memory")
; #define PG8_WAIT_L(n) asm volatile("s_waitcnt lgkmcnt(" #n ")" ::: "memory")
; template <class Epi>
; DI void gemm_phase(LAS unsigned char* lds, const Gemm g, const Order& S, const Epi& E, const int tid) {
;     ...
;         for (int t = 0; t < nt; t += 2) {
;             const bool last = (t == nt - 2);
;             const char* a1 = cA + (size_t)(t + 1) * kstep;
;             const char* a2 = last ? nA : cA + (size_t)(t + 2) * kstep; const char* b2 = last ? nB : cB + (size_t)(t + 2) * kstep;
;             const char* a3 = a2 + kstep; const char* b3 = b2 + kstep;
;             PG8_LDB(B0, 0, 0); PG8_SCHED; PG8_LDA(At, 0, 0); PG8_STAGE(PG8_SA(1, 1), a1 + hstepA, voffA);
;             PG8_WAIT_L(8); PG8_BAR; PG8_WAIT_L(0); PG8_MMA(0, 0, At, B0); PG8_BAR; PG8_SCHED;
;             PG8_LDB(B1, 0, 1); PG8_STAGE(PG8_SB(0, 0), b2, voffB);
;             PG8_BAR; PG8_WAIT_L(0); PG8_MMA(0, 1, At, B1); PG8_BAR;
;             PG8_LDA(At, 0, 1); PG8_STAGE(PG8_SA(0, 0), a2, voffA);
;             PG8_BAR; PG8_WAIT_L(0); PG8_MMA(1, 0, At, B0); PG8_BAR; PG8_SCHED;
;             PG8_STAGE(PG8_SB(0, 1), b2 + hstepB, voffB);
;             PG8_WAIT_V(6); PG8_BAR; PG8_MMA(1, 1, At, B1); PG8_BAR;
;             PG8_LDB(B0, 1, 0); PG8_SCHED; PG8_LDA(At, 1, 0); PG8_STAGE(PG8_SA(0, 1), a2 + hstepA, voffA);
;             PG8_WAIT_L(8); PG8_BAR; PG8_WAIT_L(0); PG8_MMA(0, 0, At, B0); PG8_BAR; PG8_SCHED;
;             PG8_LDB(B1, 1, 1); PG8_STAGE(PG8_SB(1, 0), b3, voffB);
;             PG8_BAR; PG8_WAIT_L(0); PG8_MMA(0, 1, At, B1); PG8_BAR;
;             PG8_LDA(At, 1, 1); PG8_STAGE(PG8_SA(1, 0), a3, voffA);
;             PG8_BAR; PG8_WAIT_L(0); PG8_MMA(1, 0, At, B0); PG8_BAR; PG8_SCHED;
;             PG8_STAGE(PG8_SB(1, 1), b3 + hstepB, voffB);
;             PG8_WAIT_V(6); PG8_BAR; PG8_MMA(1, 1, At, B1); PG8_BAR;
	s_add_u32 s78, s78, s68
	s_addc_u32 s79, s79, s69
	s_add_i32 s46, s93, s49
	v_lshl_add_u64 v[230:231], s[78:79], 0, v[0:1]
	s_mov_b32 m0, s46
	v_lshl_add_u64 v[232:233], s[78:79], 0, v[134:135]
	global_load_lds_dwordx4 v[230:231], off
	s_add_i32 m0, s46, 0x2000
	s_nop 0
	global_load_lds_dwordx4 v[232:233], off
	s_waitcnt vmcnt(6)
	s_barrier
	s_setprio 1
	v_mfma_f32_16x16x32_bf16 v[54:57], v[206:209], v[160:163], v[54:57]
	v_mfma_f32_16x16x32_bf16 v[50:53], v[214:217], v[160:163], v[50:53]
	v_mfma_f32_16x16x32_bf16 v[38:41], v[206:209], v[168:171], v[38:41]
	v_mfma_f32_16x16x32_bf16 v[34:37], v[214:217], v[168:171], v[34:37]
	v_mfma_f32_16x16x32_bf16 v[22:25], v[206:209], v[176:179], v[22:25]
	v_mfma_f32_16x16x32_bf16 v[18:21], v[214:217], v[176:179], v[18:21]
	v_mfma_f32_16x16x32_bf16 v[6:9], v[206:209], v[198:201], v[6:9]
	v_mfma_f32_16x16x32_bf16 v[2:5], v[214:217], v[198:201], v[2:5]
	v_mfma_f32_16x16x32_bf16 v[54:57], v[210:213], v[164:167], v[54:57]
	v_mfma_f32_16x16x32_bf16 v[50:53], v[218:221], v[164:167], v[50:53]
	v_mfma_f32_16x16x32_bf16 v[38:41], v[210:213], v[172:175], v[38:41]
	v_mfma_f32_16x16x32_bf16 v[34:37], v[218:221], v[172:175], v[34:37]
	v_mfma_f32_16x16x32_bf16 v[22:25], v[210:213], v[194:197], v[22:25]
	v_mfma_f32_16x16x32_bf16 v[18:21], v[218:221], v[194:197], v[18:21]
	v_mfma_f32_16x16x32_bf16 v[6:9], v[210:213], v[202:205], v[6:9]
	v_mfma_f32_16x16x32_bf16 v[2:5], v[218:221], v[202:205], v[2:5]
	s_setprio 0
	s_add_i32 s46, 0, 0x18000
	v_add_u32_e32 v152, s46, v157
	s_barrier
	ds_read_b128 v[140:143], v152
	ds_read_b128 v[144:147], v152 offset:1024
	ds_read_b128 v[148:151], v152 offset:2048
	ds_read_b128 v[152:155], v152 offset:3072
	s_add_u32 s76, s76, s66
	s_addc_u32 s77, s77, s67
	s_mov_b32 m0, s86
	v_lshl_add_u64 v[206:207], s[76:77], 0, v[130:131]
	ds_read_b128 v[160:163], v159 offset:32768
	ds_read_b128 v[164:167], v159 offset:33792
	ds_read_b128 v[168:171], v159 offset:34816
	ds_read_b128 v[172:175], v159 offset:35840
	ds_read_b128 v[176:179], v159 offset:36864
	ds_read_b128 v[194:197], v159 offset:37888
	ds_read_b128 v[198:201], v159 offset:38912
	ds_read_b128 v[202:205], v159 offset:39936
	global_load_lds_dwordx4 v[206:207], off
	v_lshl_add_u64 v[206:207], s[76:77], 0, v[132:133]
	s_mov_b32 m0, s99
	s_nop 0
	global_load_lds_dwordx4 v[206:207], off
	s_waitcnt lgkmcnt(8)
	s_barrier
	s_waitcnt lgkmcnt(0)
	s_setprio 1
	s_waitcnt lgkmcnt(0)
	v_mfma_f32_16x16x32_bf16 v[126:129], v[140:143], v[160:163], v[126:129]
	v_mfma_f32_16x16x32_bf16 v[122:125], v[148:151], v[160:163], v[122:125]
	v_mfma_f32_16x16x32_bf16 v[110:113], v[140:143], v[168:171], v[110:113]
	v_mfma_f32_16x16x32_bf16 v[106:109], v[148:151], v[168:171], v[106:109]
	v_mfma_f32_16x16x32_bf16 v[94:97], v[140:143], v[176:179], v[94:97]
	v_mfma_f32_16x16x32_bf16 v[90:93], v[148:151], v[176:179], v[90:93]
	v_mfma_f32_16x16x32_bf16 v[78:81], v[140:143], v[198:201], v[78:81]
	v_mfma_f32_16x16x32_bf16 v[74:77], v[148:151], v[198:201], v[74:77]
	v_mfma_f32_16x16x32_bf16 v[126:129], v[144:147], v[164:167], v[126:129]
	v_mfma_f32_16x16x32_bf16 v[122:125], v[152:155], v[164:167], v[122:125]
	v_mfma_f32_16x16x32_bf16 v[110:113], v[144:147], v[172:175], v[110:113]
	v_mfma_f32_16x16x32_bf16 v[106:109], v[152:155], v[172:175], v[106:109]
	v_mfma_f32_16x16x32_bf16 v[94:97], v[144:147], v[194:197], v[94:97]
	v_mfma_f32_16x16x32_bf16 v[90:93], v[152:155], v[194:197], v[90:93]
	v_mfma_f32_16x16x32_bf16 v[78:81], v[144:147], v[202:205], v[78:81]
	v_mfma_f32_16x16x32_bf16 v[74:77], v[152:155], v[202:205], v[74:77]
	s_setprio 0
	s_barrier
	s_add_i32 s76, 0, 0x1c000
	s_add_i32 s46, s46, s49
	v_add_u32_e32 v218, s76, v157
	v_lshl_add_u64 v[222:223], v[222:223], 0, s[38:39]
	s_mov_b32 m0, s46
	ds_read_b128 v[206:209], v218
	ds_read_b128 v[210:213], v218 offset:1024
	ds_read_b128 v[214:217], v218 offset:2048
	ds_read_b128 v[218:221], v218 offset:3072
	global_load_lds_dwordx4 v[222:223], off
	v_lshl_add_u64 v[222:223], v[224:225], 0, s[38:39]
	s_add_i32 m0, s46, 0x2000
	s_nop 0
	global_load_lds_dwordx4 v[222:223], off
	s_barrier
	s_waitcnt lgkmcnt(0)
	s_setprio 1
	s_waitcnt lgkmcnt(0)
	v_mfma_f32_16x16x32_bf16 v[118:121], v[206:209], v[160:163], v[118:121]
	v_mfma_f32_16x16x32_bf16 v[114:117], v[214:217], v[160:163], v[114:117]
	v_mfma_f32_16x16x32_bf16 v[102:105], v[206:209], v[168:171], v[102:105]
	v_mfma_f32_16x16x32_bf16 v[98:101], v[214:217], v[168:171], v[98:101]
	v_mfma_f32_16x16x32_bf16 v[86:89], v[206:209], v[176:179], v[86:89]
	v_mfma_f32_16x16x32_bf16 v[82:85], v[214:217], v[176:179], v[82:85]
	v_mfma_f32_16x16x32_bf16 v[70:73], v[206:209], v[198:201], v[70:73]
	v_mfma_f32_16x16x32_bf16 v[66:69], v[214:217], v[198:201], v[66:69]
	v_mfma_f32_16x16x32_bf16 v[118:121], v[210:213], v[164:167], v[118:121]
	v_mfma_f32_16x16x32_bf16 v[114:117], v[218:221], v[164:167], v[114:117]
	v_mfma_f32_16x16x32_bf16 v[102:105], v[210:213], v[172:175], v[102:105]
	v_mfma_f32_16x16x32_bf16 v[98:101], v[218:221], v[172:175], v[98:101]
	v_mfma_f32_16x16x32_bf16 v[86:89], v[210:213], v[194:197], v[86:89]
	v_mfma_f32_16x16x32_bf16 v[82:85], v[218:221], v[194:197], v[82:85]
	v_mfma_f32_16x16x32_bf16 v[70:73], v[210:213], v[202:205], v[70:73]
	v_mfma_f32_16x16x32_bf16 v[66:69], v[218:221], v[202:205], v[66:69]
	s_setprio 0
	s_mov_b32 m0, s35
	v_lshl_add_u64 v[222:223], v[226:227], 0, s[38:39]
	s_barrier
	ds_read_b128 v[160:163], v159 offset:49152
	ds_read_b128 v[164:167], v159 offset:50176
	ds_read_b128 v[168:171], v159 offset:51200
	ds_read_b128 v[172:175], v159 offset:52224
	ds_read_b128 v[176:179], v159 offset:53248
	ds_read_b128 v[194:197], v159 offset:54272
	ds_read_b128 v[198:201], v159 offset:55296
	ds_read_b128 v[202:205], v159 offset:56320
	global_load_lds_dwordx4 v[222:223], off
	v_lshl_add_u64 v[222:223], v[228:229], 0, s[38:39]
	s_mov_b32 m0, s36
	s_nop 0
	global_load_lds_dwordx4 v[222:223], off
	s_barrier
;     DI void* gp(int i) const { return (void*)(__attribute__((address_space(1))) void*)ld(i); }
; DI float bflo(unsigned w) { return __uint_as_float(w << 16); }
; DI float bfhi(unsigned w) { return __uint_as_float(w & 0xffff0000u); }
; #define PG8_LDA(dst, b, h) do { _Pragma("unroll") for (int m = 0; m < 4; ++m) _Pragma("unroll") for (int k = 0; k < 2; ++k) dst[m][k] = *(const LAS bf16x8*)(lds + PG8_SA(b, h) + aoff + m * 2048 + k * 1024); } while (0)
; template <class Epi>
; DI void gemm_phase(LAS unsigned char* lds, const Gemm g, const Order& S, const Epi& E, const int tid) {
;     ...
;             PG8_WAIT_V(6); PG8_BAR; PG8_MMA(1, 1, At, B1); PG8_BAR;
;             PG8_LDB(B0, 1, 0); PG8_SCHED; PG8_LDA(At, 1, 0); PG8_STAGE(PG8_SA(0, 1), a2 + hstepA, voffA);
;             PG8_WAIT_L(8); PG8_BAR; PG8_WAIT_L(0); PG8_MMA(0, 0, At, B0); PG8_BAR; PG8_SCHED;
;             PG8_LDB(B1, 1, 1); PG8_STAGE(PG8_SB(1, 0), b3, voffB);
;             PG8_BAR; PG8_WAIT_L(0); PG8_MMA(0, 1, At, B1); PG8_BAR;
;             PG8_LDA(At, 1, 1); PG8_STAGE(PG8_SA(1, 0), a3, voffA);
;             PG8_BAR; PG8_WAIT_L(0); PG8_MMA(1, 0, At, B0); PG8_BAR; PG8_SCHED;
;             PG8_STAGE(PG8_SB(1, 1), b3 + hstepB, voffB);
;             PG8_WAIT_V(6); PG8_BAR; PG8_MMA(1, 1, At, B1); PG8_BAR;
;         }
;         E(acc, cur, wr, wc, fr, fq);
;         if (!has_next) break;
;     DI void operator()(const f32x4 (&acc)[2][2][4][2], const Unit& u, int wr, int wc, int fr, int fq) const {
;     ...
;         } else {
;             const int col0 = u.pn * BM + wc * 32 + 8 * fq;
; #pragma unroll
;             for (int ai = 0; ai < 2; ++ai)
; #pragma unroll
;                 for (int m = 0; m < 4; ++m) { const int row = row0 + ai * HALF + m * 16; bf16_t* rowp = O + (size_t)row * DM + col0;
;                     const bf16_t* gp = Z + (size_t)row * LDZ + ZC_G + u.seg * DM + col0;
; #pragma unroll
;                     for (int bj = 0; bj < 2; ++bj) { const u32x4 gw = *(const u32x4*)(gp + bj * HALF);
;                         f32x4 v0 = acc[ai][bj][m][0], v1 = acc[ai][bj][m][1];
;                         v0[0] *= bflo(gw.x); v0[1] *= bfhi(gw.x); v0[2] *= bflo(gw.y); v0[3] *= bfhi(gw.y);
;                         v1[0] *= bflo(gw.z); v1[1] *= bfhi(gw.z); v1[2] *= bflo(gw.w); v1[3] *= bfhi(gw.w);
;                         if (u.seg > 0) { const u32x4 pw = *(const u32x4*)(rowp + bj * HALF);
	s_waitcnt lgkmcnt(0)
	s_setprio 1
	s_waitcnt lgkmcnt(0)
	v_mfma_f32_16x16x32_bf16 v[62:65], v[140:143], v[160:163], v[62:65]
	v_mfma_f32_16x16x32_bf16 v[58:61], v[148:151], v[160:163], v[58:61]
	v_mfma_f32_16x16x32_bf16 v[46:49], v[140:143], v[168:171], v[46:49]
	v_mfma_f32_16x16x32_bf16 v[42:45], v[148:151], v[168:171], v[42:45]
	v_mfma_f32_16x16x32_bf16 v[30:33], v[140:143], v[176:179], v[30:33]
	v_mfma_f32_16x16x32_bf16 v[26:29], v[148:151], v[176:179], v[26:29]
	v_mfma_f32_16x16x32_bf16 v[14:17], v[140:143], v[198:201], v[14:17]
	v_mfma_f32_16x16x32_bf16 v[10:13], v[148:151], v[198:201], v[10:13]
	v_mfma_f32_16x16x32_bf16 v[62:65], v[144:147], v[164:167], v[62:65]
	v_mfma_f32_16x16x32_bf16 v[58:61], v[152:155], v[164:167], v[58:61]
	v_mfma_f32_16x16x32_bf16 v[46:49], v[144:147], v[172:175], v[46:49]
	v_mfma_f32_16x16x32_bf16 v[42:45], v[152:155], v[172:175], v[42:45]
	v_mfma_f32_16x16x32_bf16 v[30:33], v[144:147], v[194:197], v[30:33]
	v_mfma_f32_16x16x32_bf16 v[26:29], v[152:155], v[194:197], v[26:29]
	v_mfma_f32_16x16x32_bf16 v[14:17], v[144:147], v[202:205], v[14:17]
	v_mfma_f32_16x16x32_bf16 v[10:13], v[152:155], v[202:205], v[10:13]
	s_setprio 0
	s_barrier
	s_add_i32 s46, s76, s49
	v_lshl_add_u64 v[140:141], v[230:231], 0, s[38:39]
	s_mov_b32 m0, s46
	s_nop 0
	global_load_lds_dwordx4 v[140:141], off
	v_lshl_add_u64 v[140:141], v[232:233], 0, s[38:39]
	s_add_i32 m0, s46, 0x2000
	s_nop 0
	global_load_lds_dwordx4 v[140:141], off
	s_waitcnt vmcnt(6)
	s_barrier
	s_setprio 1
	v_mfma_f32_16x16x32_bf16 v[54:57], v[206:209], v[160:163], v[54:57]
	v_mfma_f32_16x16x32_bf16 v[50:53], v[214:217], v[160:163], v[50:53]
	v_mfma_f32_16x16x32_bf16 v[38:41], v[206:209], v[168:171], v[38:41]
	v_mfma_f32_16x16x32_bf16 v[34:37], v[214:217], v[168:171], v[34:37]
	v_mfma_f32_16x16x32_bf16 v[22:25], v[206:209], v[176:179], v[22:25]
	v_mfma_f32_16x16x32_bf16 v[18:21], v[214:217], v[176:179], v[18:21]
	v_mfma_f32_16x16x32_bf16 v[6:9], v[206:209], v[198:201], v[6:9]
	v_mfma_f32_16x16x32_bf16 v[2:5], v[214:217], v[198:201], v[2:5]
	v_mfma_f32_16x16x32_bf16 v[54:57], v[210:213], v[164:167], v[54:57]
	v_mfma_f32_16x16x32_bf16 v[50:53], v[218:221], v[164:167], v[50:53]
	v_mfma_f32_16x16x32_bf16 v[38:41], v[210:213], v[172:175], v[38:41]
	v_mfma_f32_16x16x32_bf16 v[34:37], v[218:221], v[172:175], v[34:37]
	v_mfma_f32_16x16x32_bf16 v[22:25], v[210:213], v[194:197], v[22:25]
	v_mfma_f32_16x16x32_bf16 v[18:21], v[218:221], v[194:197], v[18:21]
	v_mfma_f32_16x16x32_bf16 v[6:9], v[210:213], v[202:205], v[6:9]
	v_mfma_f32_16x16x32_bf16 v[2:5], v[218:221], v[202:205], v[2:5]
	s_setprio 0
	s_add_u32 s17, s17, 0x100
	s_addc_u32 vcc_lo, vcc_lo, 0
	s_add_u32 s0, s0, 0x100
	s_addc_u32 s1, s1, 0
	s_cmp_ge_u32 vcc_hi, s15
	s_mov_b32 s76, vcc_hi
	s_barrier
	s_cbranch_scc0 .LBB0_629
	v_lshl_add_u32 v140, s50, 8, v156
	v_ashrrev_i32_e32 v141, 31, v140
	s_cmp_lt_i32 s83, 1
	s_mov_b64 s[0:1], -1
	s_cbranch_scc1 .LBB0_668
	s_cmp_lg_u32 s83, 1
	s_cbranch_scc0 .LBB0_665
	v_lshl_or_b32 v142, s96, 8, v158
	v_lshlrev_b32_e32 v142, 1, v142
	s_lshl_b32 s0, s51, 12
	s_add_i32 s0, s0, 0x2a80
	s_add_u32 s76, s60, s0
	s_addc_u32 s77, s61, 0
	v_mad_u32_u24 v143, v140, s92, v142
	v_lshl_add_u32 v144, v140, 12, v142
	v_mov_b32_e32 v145, v143
	v_add_u32_e32 v146, 0x5c000, v143
	v_mov_b32_e32 v206, v144
	v_add_u32_e32 v207, 0x10000, v144
	global_load_dwordx4 v[160:163], v145, s[76:77]
	global_load_dwordx4 v[164:167], v145, s[76:77] offset:256
	global_load_dwordx4 v[168:171], v146, s[76:77]
	global_load_dwordx4 v[172:175], v146, s[76:77] offset:256
	s_cmp_lt_i32 s51, 1
	s_cbranch_scc1 .Lepi2_zero_0
	global_load_dwordx4 v[194:197], v206, s[56:57]
	global_load_dwordx4 v[198:201], v206, s[56:57] offset:256
	global_load_dwordx4 v[202:205], v207, s[56:57]
	global_load_dwordx4 v[176:179], v207, s[56:57] offset:256
	s_branch .Lepi2_go_0
.Lepi2_zero_0:
	v_mov_b32_e32 v194, 0
	v_mov_b32_e32 v195, 0
	v_mov_b32_e32 v196, 0
	v_mov_b32_e32 v197, 0
	v_mov_b32_e32 v198, 0
	v_mov_b32_e32 v199, 0
	v_mov_b32_e32 v200, 0
	v_mov_b32_e32 v201, 0
	v_mov_b32_e32 v202, 0
	v_mov_b32_e32 v203, 0
	v_mov_b32_e32 v204, 0
	v_mov_b32_e32 v205, 0
	v_mov_b32_e32 v176, 0
	v_mov_b32_e32 v177, 0
	v_mov_b32_e32 v178, 0
	v_mov_b32_e32 v179, 0
;     DI void* gp(int i) const { return (void*)(__attribute__((address_space(1))) void*)ld(i); }
; DI float bflo(unsigned w) { return __uint_as_float(w << 16); }
; DI float bfhi(unsigned w) { return __uint_as_float(w & 0xffff0000u); }
; DI u32x4 pack8(f32x4 v0, f32x4 v1) { u32x4 w; w.x = cvtpk(v0[0], v0[1]); w.y = cvtpk(v0[2], v0[3]); w.z = cvtpk(v1[0], v1[1]); w.w = cvtpk(v1[2], v1[3]); return w; }
;     DI void operator()(const f32x4 (&acc)[2][2][4][2], const Unit& u, int wr, int wc, int fr, int fq) const {
;     ...
;             for (int ai = 0; ai < 2; ++ai)
; #pragma unroll
;                 for (int m = 0; m < 4; ++m) { const int row = row0 + ai * HALF + m * 16; bf16_t* rowp = O + (size_t)row * DM + col0;
;                     const bf16_t* gp = Z + (size_t)row * LDZ + ZC_G + u.seg * DM + col0;
; #pragma unroll
;                     for (int bj = 0; bj < 2; ++bj) { const u32x4 gw = *(const u32x4*)(gp + bj * HALF);
;                         f32x4 v0 = acc[ai][bj][m][0], v1 = acc[ai][bj][m][1];
;                         v0[0] *= bflo(gw.x); v0[1] *= bfhi(gw.x); v0[2] *= bflo(gw.y); v0[3] *= bfhi(gw.y);
;                         v1[0] *= bflo(gw.z); v1[1] *= bfhi(gw.z); v1[2] *= bflo(gw.w); v1[3] *= bfhi(gw.w);
;                         if (u.seg > 0) { const u32x4 pw = *(const u32x4*)(rowp + bj * HALF);
;                             v0[0] += bflo(pw.x); v0[1] += bfhi(pw.x); v0[2] += bflo(pw.y); v0[3] += bfhi(pw.y);
;                             v1[0] += bflo(pw.z); v1[1] += bfhi(pw.z); v1[2] += bflo(pw.w); v1[3] += bfhi(pw.w); }
;                         *(u32x4*)(rowp + bj * HALF) = pack8(v0, v1); } }
.Lepi2_go_0:
	s_waitcnt vmcnt(0)
	v_lshlrev_b32_e32 v147, 16, v160
	v_and_b32_e32 v148, 0xffff0000, v160
	v_lshlrev_b32_e32 v149, 16, v161
	v_and_b32_e32 v150, 0xffff0000, v161
	v_lshlrev_b32_e32 v151, 16, v162
	v_and_b32_e32 v152, 0xffff0000, v162
	v_lshlrev_b32_e32 v153, 16, v163
	v_and_b32_e32 v154, 0xffff0000, v163
	v_mul_f32_e32 v126, v126, v147
	v_mul_f32_e32 v127, v127, v148
	v_mul_f32_e32 v128, v128, v149
	v_mul_f32_e32 v129, v129, v150
	v_mul_f32_e32 v122, v122, v151
	v_mul_f32_e32 v123, v123, v152
	v_mul_f32_e32 v124, v124, v153
	v_mul_f32_e32 v125, v125, v154
	v_lshlrev_b32_e32 v147, 16, v194
	v_and_b32_e32 v148, 0xffff0000, v194
	v_lshlrev_b32_e32 v149, 16, v195
	v_and_b32_e32 v150, 0xffff0000, v195
	v_lshlrev_b32_e32 v151, 16, v196
	v_and_b32_e32 v152, 0xffff0000, v196
	v_lshlrev_b32_e32 v153, 16, v197
	v_and_b32_e32 v154, 0xffff0000, v197
	v_add_f32_e32 v126, v126, v147
	v_add_f32_e32 v127, v127, v148
	v_add_f32_e32 v128, v128, v149
	v_add_f32_e32 v129, v129, v150
	v_add_f32_e32 v122, v122, v151
	v_add_f32_e32 v123, v123, v152
	v_add_f32_e32 v124, v124, v153
	v_add_f32_e32 v125, v125, v154
	v_cvt_pk_bf16_f32 v234, v126, v127
	v_cvt_pk_bf16_f32 v235, v128, v129
	v_cvt_pk_bf16_f32 v236, v122, v123
	v_cvt_pk_bf16_f32 v237, v124, v125
	global_store_dwordx4 v206, v[234:237], s[56:57]
	v_lshlrev_b32_e32 v147, 16, v164
	v_and_b32_e32 v148, 0xffff0000, v164
	v_lshlrev_b32_e32 v149, 16, v165
	v_and_b32_e32 v150, 0xffff0000, v165
	v_lshlrev_b32_e32 v151, 16, v166
	v_and_b32_e32 v152, 0xffff0000, v166
	v_lshlrev_b32_e32 v153, 16, v167
	v_and_b32_e32 v154, 0xffff0000, v167
	v_mul_f32_e32 v118, v118, v147
	v_mul_f32_e32 v119, v119, v148
	v_mul_f32_e32 v120, v120, v149
	v_mul_f32_e32 v121, v121, v150
	v_mul_f32_e32 v114, v114, v151
	v_mul_f32_e32 v115, v115, v152
	v_mul_f32_e32 v116, v116, v153
	v_mul_f32_e32 v117, v117, v154
	v_lshlrev_b32_e32 v147, 16, v198
	v_and_b32_e32 v148, 0xffff0000, v198
	v_lshlrev_b32_e32 v149, 16, v199
	v_and_b32_e32 v150, 0xffff0000, v199
	v_lshlrev_b32_e32 v151, 16, v200
	v_and_b32_e32 v152, 0xffff0000, v200
	v_lshlrev_b32_e32 v153, 16, v201
	v_and_b32_e32 v154, 0xffff0000, v201
	v_add_f32_e32 v118, v118, v147
	v_add_f32_e32 v119, v119, v148
	v_add_f32_e32 v120, v120, v149
	v_add_f32_e32 v121, v121, v150
	v_add_f32_e32 v114, v114, v151
	v_add_f32_e32 v115, v115, v152
	v_add_f32_e32 v116, v116, v153
	v_add_f32_e32 v117, v117, v154
	v_cvt_pk_bf16_f32 v238, v118, v119
	v_cvt_pk_bf16_f32 v239, v120, v121
	v_cvt_pk_bf16_f32 v240, v114, v115
	v_cvt_pk_bf16_f32 v241, v116, v117
	global_store_dwordx4 v206, v[238:241], s[56:57] offset:256
	v_lshlrev_b32_e32 v147, 16, v168
	v_and_b32_e32 v148, 0xffff0000, v168
	v_lshlrev_b32_e32 v149, 16, v169
	v_and_b32_e32 v150, 0xffff0000, v169
	v_lshlrev_b32_e32 v151, 16, v170
	v_and_b32_e32 v152, 0xffff0000, v170
	v_lshlrev_b32_e32 v153, 16, v171
	v_and_b32_e32 v154, 0xffff0000, v171
	v_mul_f32_e32 v110, v110, v147
	v_mul_f32_e32 v111, v111, v148
	v_mul_f32_e32 v112, v112, v149
	v_mul_f32_e32 v113, v113, v150
	v_mul_f32_e32 v106, v106, v151
	v_mul_f32_e32 v107, v107, v152
	v_mul_f32_e32 v108, v108, v153
	v_mul_f32_e32 v109, v109, v154
	v_lshlrev_b32_e32 v147, 16, v202
	v_and_b32_e32 v148, 0xffff0000, v202
	v_lshlrev_b32_e32 v149, 16, v203
	v_and_b32_e32 v150, 0xffff0000, v203
	v_lshlrev_b32_e32 v151, 16, v204
	v_and_b32_e32 v152, 0xffff0000, v204
	v_lshlrev_b32_e32 v153, 16, v205
	v_and_b32_e32 v154, 0xffff0000, v205
	v_add_f32_e32 v110, v110, v147
	v_add_f32_e32 v111, v111, v148
	v_add_f32_e32 v112, v112, v149
	v_add_f32_e32 v113, v113, v150
	v_add_f32_e32 v106, v106, v151
	v_add_f32_e32 v107, v107, v152
	v_add_f32_e32 v108, v108, v153
	v_add_f32_e32 v109, v109, v154
	v_cvt_pk_bf16_f32 v234, v110, v111
	v_cvt_pk_bf16_f32 v235, v112, v113
	v_cvt_pk_bf16_f32 v236, v106, v107
	v_cvt_pk_bf16_f32 v237, v108, v109
	global_store_dwordx4 v207, v[234:237], s[56:57]
	v_lshlrev_b32_e32 v147, 16, v172
	v_and_b32_e32 v148, 0xffff0000, v172
	v_lshlrev_b32_e32 v149, 16, v173
	v_and_b32_e32 v150, 0xffff0000, v173
	v_lshlrev_b32_e32 v151, 16, v174
	v_and_b32_e32 v152, 0xffff0000, v174
	v_lshlrev_b32_e32 v153, 16, v175
	v_and_b32_e32 v154, 0xffff0000, v175
	v_mul_f32_e32 v102, v102, v147
	v_mul_f32_e32 v103, v103, v148
	v_mul_f32_e32 v104, v104, v149
	v_mul_f32_e32 v105, v105, v150
	v_mul_f32_e32 v98, v98, v151
	v_mul_f32_e32 v99, v99, v152
	v_mul_f32_e32 v100, v100, v153
	v_mul_f32_e32 v101, v101, v154
	v_lshlrev_b32_e32 v147, 16, v176
	v_and_b32_e32 v148, 0xffff0000, v176
	v_lshlrev_b32_e32 v149, 16, v177
	v_and_b32_e32 v150, 0xffff0000, v177
	v_lshlrev_b32_e32 v151, 16, v178
	v_and_b32_e32 v152, 0xffff0000, v178
	v_lshlrev_b32_e32 v153, 16, v179
	v_and_b32_e32 v154, 0xffff0000, v179
	v_add_f32_e32 v102, v102, v147
	v_add_f32_e32 v103, v103, v148
	v_add_f32_e32 v104, v104, v149
	v_add_f32_e32 v105, v105, v150
	v_add_f32_e32 v98, v98, v151
	v_add_f32_e32 v99, v99, v152
	v_add_f32_e32 v100, v100, v153
	v_add_f32_e32 v101, v101, v154
	v_cvt_pk_bf16_f32 v238, v102, v103
	v_cvt_pk_bf16_f32 v239, v104, v105
	v_cvt_pk_bf16_f32 v240, v98, v99
	v_cvt_pk_bf16_f32 v241, v100, v101
	global_store_dwordx4 v207, v[238:241], s[56:57] offset:256
	v_add_u32_e32 v145, 0xb8000, v143
	v_add_u32_e32 v146, 0x114000, v143
	v_add_u32_e32 v206, 0x20000, v144
	v_add_u32_e32 v207, 0x30000, v144
	global_load_dwordx4 v[160:163], v145, s[76:77]
	global_load_dwordx4 v[164:167], v145, s[76:77] offset:256
	global_load_dwordx4 v[168:171], v146, s[76:77]
	global_load_dwordx4 v[172:175], v146, s[76:77] offset:256
	s_cmp_lt_i32 s51, 1
	s_cbranch_scc1 .Lepi2_zero_1
	global_load_dwordx4 v[194:197], v206, s[56:57]
	global_load_dwordx4 v[198:201], v206, s[56:57] offset:256
	global_load_dwordx4 v[202:205], v207, s[56:57]
	global_load_dwordx4 v[176:179], v207, s[56:57] offset:256
	s_branch .Lepi2_go_1

;     DI void* gp(int i) const { return (void*)(__attribute__((address_space(1))) void*)ld(i); }
; DI float bflo(unsigned w) { return __uint_as_float(w << 16); }
; DI float bfhi(unsigned w) { return __uint_as_float(w & 0xffff0000u); }
; DI u32x4 pack8(f32x4 v0, f32x4 v1) { u32x4 w; w.x = cvtpk(v0[0], v0[1]); w.y = cvtpk(v0[2], v0[3]); w.z = cvtpk(v1[0], v1[1]); w.w = cvtpk(v1[2], v1[3]); return w; }
;     DI void operator()(const f32x4 (&acc)[2][2][4][2], const Unit& u, int wr, int wc, int fr, int fq) const {
;     ...
;             for (int ai = 0; ai < 2; ++ai)
; #pragma unroll
;                 for (int m = 0; m < 4; ++m) { const int row = row0 + ai * HALF + m * 16; bf16_t* rowp = O + (size_t)row * DM + col0;
;                     const bf16_t* gp = Z + (size_t)row * LDZ + ZC_G + u.seg * DM + col0;
; #pragma unroll
;                     for (int bj = 0; bj < 2; ++bj) { const u32x4 gw = *(const u32x4*)(gp + bj * HALF);
;                         f32x4 v0 = acc[ai][bj][m][0], v1 = acc[ai][bj][m][1];
;                         v0[0] *= bflo(gw.x); v0[1] *= bfhi(gw.x); v0[2] *= bflo(gw.y); v0[3] *= bfhi(gw.y);
;                         v1[0] *= bflo(gw.z); v1[1] *= bfhi(gw.z); v1[2] *= bflo(gw.w); v1[3] *= bfhi(gw.w);
;                         if (u.seg > 0) { const u32x4 pw = *(const u32x4*)(rowp + bj * HALF);
;                             v0[0] += bflo(pw.x); v0[1] += bfhi(pw.x); v0[2] += bflo(pw.y); v0[3] += bfhi(pw.y);
;                             v1[0] += bflo(pw.z); v1[1] += bfhi(pw.z); v1[2] += bflo(pw.w); v1[3] += bfhi(pw.w); }
;                         *(u32x4*)(rowp + bj * HALF) = pack8(v0, v1); } }
.Lepi2_go_1:
	s_waitcnt vmcnt(0)
	v_lshlrev_b32_e32 v147, 16, v160
	v_and_b32_e32 v148, 0xffff0000, v160
	v_lshlrev_b32_e32 v149, 16, v161
	v_and_b32_e32 v150, 0xffff0000, v161
	v_lshlrev_b32_e32 v151, 16, v162
	v_and_b32_e32 v152, 0xffff0000, v162
	v_lshlrev_b32_e32 v153, 16, v163
	v_and_b32_e32 v154, 0xffff0000, v163
	v_mul_f32_e32 v94, v94, v147
	v_mul_f32_e32 v95, v95, v148
	v_mul_f32_e32 v96, v96, v149
	v_mul_f32_e32 v97, v97, v150
	v_mul_f32_e32 v90, v90, v151
	v_mul_f32_e32 v91, v91, v152
	v_mul_f32_e32 v92, v92, v153
	v_mul_f32_e32 v93, v93, v154
	v_lshlrev_b32_e32 v147, 16, v194
	v_and_b32_e32 v148, 0xffff0000, v194
	v_lshlrev_b32_e32 v149, 16, v195
	v_and_b32_e32 v150, 0xffff0000, v195
	v_lshlrev_b32_e32 v151, 16, v196
	v_and_b32_e32 v152, 0xffff0000, v196
	v_lshlrev_b32_e32 v153, 16, v197
	v_and_b32_e32 v154, 0xffff0000, v197
	v_add_f32_e32 v94, v94, v147
	v_add_f32_e32 v95, v95, v148
	v_add_f32_e32 v96, v96, v149
	v_add_f32_e32 v97, v97, v150
	v_add_f32_e32 v90, v90, v151
	v_add_f32_e32 v91, v91, v152
	v_add_f32_e32 v92, v92, v153
	v_add_f32_e32 v93, v93, v154
	v_cvt_pk_bf16_f32 v234, v94, v95
	v_cvt_pk_bf16_f32 v235, v96, v97
	v_cvt_pk_bf16_f32 v236, v90, v91
	v_cvt_pk_bf16_f32 v237, v92, v93
	global_store_dwordx4 v206, v[234:237], s[56:57]
	v_lshlrev_b32_e32 v147, 16, v164
	v_and_b32_e32 v148, 0xffff0000, v164
	v_lshlrev_b32_e32 v149, 16, v165
	v_and_b32_e32 v150, 0xffff0000, v165
	v_lshlrev_b32_e32 v151, 16, v166
	v_and_b32_e32 v152, 0xffff0000, v166
	v_lshlrev_b32_e32 v153, 16, v167
	v_and_b32_e32 v154, 0xffff0000, v167
	v_mul_f32_e32 v86, v86, v147
	v_mul_f32_e32 v87, v87, v148
	v_mul_f32_e32 v88, v88, v149
	v_mul_f32_e32 v89, v89, v150
	v_mul_f32_e32 v82, v82, v151
	v_mul_f32_e32 v83, v83, v152
	v_mul_f32_e32 v84, v84, v153
	v_mul_f32_e32 v85, v85, v154
	v_lshlrev_b32_e32 v147, 16, v198
	v_and_b32_e32 v148, 0xffff0000, v198
	v_lshlrev_b32_e32 v149, 16, v199
	v_and_b32_e32 v150, 0xffff0000, v199
	v_lshlrev_b32_e32 v151, 16, v200
	v_and_b32_e32 v152, 0xffff0000, v200
	v_lshlrev_b32_e32 v153, 16, v201
	v_and_b32_e32 v154, 0xffff0000, v201
	v_add_f32_e32 v86, v86, v147
	v_add_f32_e32 v87, v87, v148
	v_add_f32_e32 v88, v88, v149
	v_add_f32_e32 v89, v89, v150
	v_add_f32_e32 v82, v82, v151
	v_add_f32_e32 v83, v83, v152
	v_add_f32_e32 v84, v84, v153
	v_add_f32_e32 v85, v85, v154
	v_cvt_pk_bf16_f32 v238, v86, v87
	v_cvt_pk_bf16_f32 v239, v88, v89
	v_cvt_pk_bf16_f32 v240, v82, v83
	v_cvt_pk_bf16_f32 v241, v84, v85
	global_store_dwordx4 v206, v[238:241], s[56:57] offset:256
	v_lshlrev_b32_e32 v147, 16, v168
	v_and_b32_e32 v148, 0xffff0000, v168
	v_lshlrev_b32_e32 v149, 16, v169
	v_and_b32_e32 v150, 0xffff0000, v169
	v_lshlrev_b32_e32 v151, 16, v170
	v_and_b32_e32 v152, 0xffff0000, v170
	v_lshlrev_b32_e32 v153, 16, v171
	v_and_b32_e32 v154, 0xffff0000, v171
	v_mul_f32_e32 v78, v78, v147
	v_mul_f32_e32 v79, v79, v148
	v_mul_f32_e32 v80, v80, v149
	v_mul_f32_e32 v81, v81, v150
	v_mul_f32_e32 v74, v74, v151
	v_mul_f32_e32 v75, v75, v152
	v_mul_f32_e32 v76, v76, v153
	v_mul_f32_e32 v77, v77, v154
	v_lshlrev_b32_e32 v147, 16, v202
	v_and_b32_e32 v148, 0xffff0000, v202
	v_lshlrev_b32_e32 v149, 16, v203
	v_and_b32_e32 v150, 0xffff0000, v203
	v_lshlrev_b32_e32 v151, 16, v204
	v_and_b32_e32 v152, 0xffff0000, v204
	v_lshlrev_b32_e32 v153, 16, v205
	v_and_b32_e32 v154, 0xffff0000, v205
	v_add_f32_e32 v78, v78, v147
	v_add_f32_e32 v79, v79, v148
	v_add_f32_e32 v80, v80, v149
	v_add_f32_e32 v81, v81, v150
	v_add_f32_e32 v74, v74, v151
	v_add_f32_e32 v75, v75, v152
	v_add_f32_e32 v76, v76, v153
	v_add_f32_e32 v77, v77, v154
	v_cvt_pk_bf16_f32 v234, v78, v79
	v_cvt_pk_bf16_f32 v235, v80, v81
	v_cvt_pk_bf16_f32 v236, v74, v75
	v_cvt_pk_bf16_f32 v237, v76, v77
	global_store_dwordx4 v207, v[234:237], s[56:57]
	v_lshlrev_b32_e32 v147, 16, v172
	v_and_b32_e32 v148, 0xffff0000, v172
	v_lshlrev_b32_e32 v149, 16, v173
	v_and_b32_e32 v150, 0xffff0000, v173
	v_lshlrev_b32_e32 v151, 16, v174
	v_and_b32_e32 v152, 0xffff0000, v174
	v_lshlrev_b32_e32 v153, 16, v175
	v_and_b32_e32 v154, 0xffff0000, v175
	v_mul_f32_e32 v70, v70, v147
	v_mul_f32_e32 v71, v71, v148
	v_mul_f32_e32 v72, v72, v149
	v_mul_f32_e32 v73, v73, v150
	v_mul_f32_e32 v66, v66, v151
	v_mul_f32_e32 v67, v67, v152
	v_mul_f32_e32 v68, v68, v153
	v_mul_f32_e32 v69, v69, v154
	v_lshlrev_b32_e32 v147, 16, v176
	v_and_b32_e32 v148, 0xffff0000, v176
	v_lshlrev_b32_e32 v149, 16, v177
	v_and_b32_e32 v150, 0xffff0000, v177
	v_lshlrev_b32_e32 v151, 16, v178
	v_and_b32_e32 v152, 0xffff0000, v178
	v_lshlrev_b32_e32 v153, 16, v179
	v_and_b32_e32 v154, 0xffff0000, v179
	v_add_f32_e32 v70, v70, v147
	v_add_f32_e32 v71, v71, v148
	v_add_f32_e32 v72, v72, v149
	v_add_f32_e32 v73, v73, v150
	v_add_f32_e32 v66, v66, v151
	v_add_f32_e32 v67, v67, v152
	v_add_f32_e32 v68, v68, v153
	v_add_f32_e32 v69, v69, v154
	v_cvt_pk_bf16_f32 v238, v70, v71
	v_cvt_pk_bf16_f32 v239, v72, v73
	v_cvt_pk_bf16_f32 v240, v66, v67
	v_cvt_pk_bf16_f32 v241, v68, v69
	global_store_dwordx4 v207, v[238:241], s[56:57] offset:256
	v_add_u32_e32 v145, 0x2e0000, v143
	v_add_u32_e32 v146, 0x33c000, v143
	v_add_u32_e32 v206, 0x80000, v144
	v_add_u32_e32 v207, 0x90000, v144
	global_load_dwordx4 v[160:163], v145, s[76:77]
	global_load_dwordx4 v[164:167], v145, s[76:77] offset:256
	global_load_dwordx4 v[168:171], v146, s[76:77]
	global_load_dwordx4 v[172:175], v146, s[76:77] offset:256
	s_cmp_lt_i32 s51, 1
	s_cbranch_scc1 .Lepi2_zero_2
	global_load_dwordx4 v[194:197], v206, s[56:57]
	global_load_dwordx4 v[198:201], v206, s[56:57] offset:256
	global_load_dwordx4 v[202:205], v207, s[56:57]
	global_load_dwordx4 v[176:179], v207, s[56:57] offset:256
	s_branch .Lepi2_go_2

;     DI void* gp(int i) const { return (void*)(__attribute__((address_space(1))) void*)ld(i); }
; DI float bflo(unsigned w) { return __uint_as_float(w << 16); }
; DI float bfhi(unsigned w) { return __uint_as_float(w & 0xffff0000u); }
; DI u32x4 pack8(f32x4 v0, f32x4 v1) { u32x4 w; w.x = cvtpk(v0[0], v0[1]); w.y = cvtpk(v0[2], v0[3]); w.z = cvtpk(v1[0], v1[1]); w.w = cvtpk(v1[2], v1[3]); return w; }
;     DI void operator()(const f32x4 (&acc)[2][2][4][2], const Unit& u, int wr, int wc, int fr, int fq) const {
;     ...
;             for (int ai = 0; ai < 2; ++ai)
; #pragma unroll
;                 for (int m = 0; m < 4; ++m) { const int row = row0 + ai * HALF + m * 16; bf16_t* rowp = O + (size_t)row * DM + col0;
;                     const bf16_t* gp = Z + (size_t)row * LDZ + ZC_G + u.seg * DM + col0;
; #pragma unroll
;                     for (int bj = 0; bj < 2; ++bj) { const u32x4 gw = *(const u32x4*)(gp + bj * HALF);
;                         f32x4 v0 = acc[ai][bj][m][0], v1 = acc[ai][bj][m][1];
;                         v0[0] *= bflo(gw.x); v0[1] *= bfhi(gw.x); v0[2] *= bflo(gw.y); v0[3] *= bfhi(gw.y);
;                         v1[0] *= bflo(gw.z); v1[1] *= bfhi(gw.z); v1[2] *= bflo(gw.w); v1[3] *= bfhi(gw.w);
;                         if (u.seg > 0) { const u32x4 pw = *(const u32x4*)(rowp + bj * HALF);
;                             v0[0] += bflo(pw.x); v0[1] += bfhi(pw.x); v0[2] += bflo(pw.y); v0[3] += bfhi(pw.y);
;                             v1[0] += bflo(pw.z); v1[1] += bfhi(pw.z); v1[2] += bflo(pw.w); v1[3] += bfhi(pw.w); }
;                         *(u32x4*)(rowp + bj * HALF) = pack8(v0, v1); } }
.Lepi2_go_2:
	s_waitcnt vmcnt(0)
	v_lshlrev_b32_e32 v147, 16, v160
	v_and_b32_e32 v148, 0xffff0000, v160
	v_lshlrev_b32_e32 v149, 16, v161
	v_and_b32_e32 v150, 0xffff0000, v161
	v_lshlrev_b32_e32 v151, 16, v162
	v_and_b32_e32 v152, 0xffff0000, v162
	v_lshlrev_b32_e32 v153, 16, v163
	v_and_b32_e32 v154, 0xffff0000, v163
	v_mul_f32_e32 v62, v62, v147
	v_mul_f32_e32 v63, v63, v148
	v_mul_f32_e32 v64, v64, v149
	v_mul_f32_e32 v65, v65, v150
	v_mul_f32_e32 v58, v58, v151
	v_mul_f32_e32 v59, v59, v152
	v_mul_f32_e32 v60, v60, v153
	v_mul_f32_e32 v61, v61, v154
	v_lshlrev_b32_e32 v147, 16, v194
	v_and_b32_e32 v148, 0xffff0000, v194
	v_lshlrev_b32_e32 v149, 16, v195
	v_and_b32_e32 v150, 0xffff0000, v195
	v_lshlrev_b32_e32 v151, 16, v196
	v_and_b32_e32 v152, 0xffff0000, v196
	v_lshlrev_b32_e32 v153, 16, v197
	v_and_b32_e32 v154, 0xffff0000, v197
	v_add_f32_e32 v62, v62, v147
	v_add_f32_e32 v63, v63, v148
	v_add_f32_e32 v64, v64, v149
	v_add_f32_e32 v65, v65, v150
	v_add_f32_e32 v58, v58, v151
	v_add_f32_e32 v59, v59, v152
	v_add_f32_e32 v60, v60, v153
	v_add_f32_e32 v61, v61, v154
	v_cvt_pk_bf16_f32 v234, v62, v63
	v_cvt_pk_bf16_f32 v235, v64, v65
	v_cvt_pk_bf16_f32 v236, v58, v59
	v_cvt_pk_bf16_f32 v237, v60, v61
	global_store_dwordx4 v206, v[234:237], s[56:57]
	v_lshlrev_b32_e32 v147, 16, v164
	v_and_b32_e32 v148, 0xffff0000, v164
	v_lshlrev_b32_e32 v149, 16, v165
	v_and_b32_e32 v150, 0xffff0000, v165
	v_lshlrev_b32_e32 v151, 16, v166
	v_and_b32_e32 v152, 0xffff0000, v166
	v_lshlrev_b32_e32 v153, 16, v167
	v_and_b32_e32 v154, 0xffff0000, v167
	v_mul_f32_e32 v54, v54, v147
	v_mul_f32_e32 v55, v55, v148
	v_mul_f32_e32 v56, v56, v149
	v_mul_f32_e32 v57, v57, v150
	v_mul_f32_e32 v50, v50, v151
	v_mul_f32_e32 v51, v51, v152
	v_mul_f32_e32 v52, v52, v153
	v_mul_f32_e32 v53, v53, v154
	v_lshlrev_b32_e32 v147, 16, v198
	v_and_b32_e32 v148, 0xffff0000, v198
	v_lshlrev_b32_e32 v149, 16, v199
	v_and_b32_e32 v150, 0xffff0000, v199
	v_lshlrev_b32_e32 v151, 16, v200
	v_and_b32_e32 v152, 0xffff0000, v200
	v_lshlrev_b32_e32 v153, 16, v201
	v_and_b32_e32 v154, 0xffff0000, v201
	v_add_f32_e32 v54, v54, v147
	v_add_f32_e32 v55, v55, v148
	v_add_f32_e32 v56, v56, v149
	v_add_f32_e32 v57, v57, v150
	v_add_f32_e32 v50, v50, v151
	v_add_f32_e32 v51, v51, v152
	v_add_f32_e32 v52, v52, v153
	v_add_f32_e32 v53, v53, v154
	v_cvt_pk_bf16_f32 v238, v54, v55
	v_cvt_pk_bf16_f32 v239, v56, v57
	v_cvt_pk_bf16_f32 v240, v50, v51
	v_cvt_pk_bf16_f32 v241, v52, v53
	global_store_dwordx4 v206, v[238:241], s[56:57] offset:256
	v_lshlrev_b32_e32 v147, 16, v168
	v_and_b32_e32 v148, 0xffff0000, v168
	v_lshlrev_b32_e32 v149, 16, v169
	v_and_b32_e32 v150, 0xffff0000, v169
	v_lshlrev_b32_e32 v151, 16, v170
	v_and_b32_e32 v152, 0xffff0000, v170
	v_lshlrev_b32_e32 v153, 16, v171
	v_and_b32_e32 v154, 0xffff0000, v171
	v_mul_f32_e32 v46, v46, v147
	v_mul_f32_e32 v47, v47, v148
	v_mul_f32_e32 v48, v48, v149
	v_mul_f32_e32 v49, v49, v150
	v_mul_f32_e32 v42, v42, v151
	v_mul_f32_e32 v43, v43, v152
	v_mul_f32_e32 v44, v44, v153
	v_mul_f32_e32 v45, v45, v154
	v_lshlrev_b32_e32 v147, 16, v202
	v_and_b32_e32 v148, 0xffff0000, v202
	v_lshlrev_b32_e32 v149, 16, v203
	v_and_b32_e32 v150, 0xffff0000, v203
	v_lshlrev_b32_e32 v151, 16, v204
	v_and_b32_e32 v152, 0xffff0000, v204
	v_lshlrev_b32_e32 v153, 16, v205
	v_and_b32_e32 v154, 0xffff0000, v205
	v_add_f32_e32 v46, v46, v147
	v_add_f32_e32 v47, v47, v148
	v_add_f32_e32 v48, v48, v149
	v_add_f32_e32 v49, v49, v150
	v_add_f32_e32 v42, v42, v151
	v_add_f32_e32 v43, v43, v152
	v_add_f32_e32 v44, v44, v153
	v_add_f32_e32 v45, v45, v154
	v_cvt_pk_bf16_f32 v234, v46, v47
	v_cvt_pk_bf16_f32 v235, v48, v49
	v_cvt_pk_bf16_f32 v236, v42, v43
	v_cvt_pk_bf16_f32 v237, v44, v45
	global_store_dwordx4 v207, v[234:237], s[56:57]
	v_lshlrev_b32_e32 v147, 16, v172
	v_and_b32_e32 v148, 0xffff0000, v172
	v_lshlrev_b32_e32 v149, 16, v173
	v_and_b32_e32 v150, 0xffff0000, v173
	v_lshlrev_b32_e32 v151, 16, v174
	v_and_b32_e32 v152, 0xffff0000, v174
	v_lshlrev_b32_e32 v153, 16, v175
	v_and_b32_e32 v154, 0xffff0000, v175
	v_mul_f32_e32 v38, v38, v147
	v_mul_f32_e32 v39, v39, v148
	v_mul_f32_e32 v40, v40, v149
	v_mul_f32_e32 v41, v41, v150
	v_mul_f32_e32 v34, v34, v151
	v_mul_f32_e32 v35, v35, v152
	v_mul_f32_e32 v36, v36, v153
	v_mul_f32_e32 v37, v37, v154
	v_lshlrev_b32_e32 v147, 16, v176
	v_and_b32_e32 v148, 0xffff0000, v176
	v_lshlrev_b32_e32 v149, 16, v177
	v_and_b32_e32 v150, 0xffff0000, v177
	v_lshlrev_b32_e32 v151, 16, v178
	v_and_b32_e32 v152, 0xffff0000, v178
	v_lshlrev_b32_e32 v153, 16, v179
	v_and_b32_e32 v154, 0xffff0000, v179
	v_add_f32_e32 v38, v38, v147
	v_add_f32_e32 v39, v39, v148
	v_add_f32_e32 v40, v40, v149
	v_add_f32_e32 v41, v41, v150
	v_add_f32_e32 v34, v34, v151
	v_add_f32_e32 v35, v35, v152
	v_add_f32_e32 v36, v36, v153
	v_add_f32_e32 v37, v37, v154
	v_cvt_pk_bf16_f32 v238, v38, v39
	v_cvt_pk_bf16_f32 v239, v40, v41
	v_cvt_pk_bf16_f32 v240, v34, v35
	v_cvt_pk_bf16_f32 v241, v36, v37
	global_store_dwordx4 v207, v[238:241], s[56:57] offset:256
	v_add_u32_e32 v145, 0x398000, v143
	v_add_u32_e32 v146, 0x3f4000, v143
	v_add_u32_e32 v206, 0xa0000, v144
	v_add_u32_e32 v207, 0xb0000, v144
	global_load_dwordx4 v[160:163], v145, s[76:77]
	global_load_dwordx4 v[164:167], v145, s[76:77] offset:256
	global_load_dwordx4 v[168:171], v146, s[76:77]
	global_load_dwordx4 v[172:175], v146, s[76:77] offset:256
	s_cmp_lt_i32 s51, 1
	s_cbranch_scc1 .Lepi2_zero_3
	global_load_dwordx4 v[194:197], v206, s[56:57]
	global_load_dwordx4 v[198:201], v206, s[56:57] offset:256
	global_load_dwordx4 v[202:205], v207, s[56:57]
	global_load_dwordx4 v[176:179], v207, s[56:57] offset:256
	s_branch .Lepi2_go_3

;     DI void* gp(int i) const { return (void*)(__attribute__((address_space(1))) void*)ld(i); }
; DI float bflo(unsigned w) { return __uint_as_float(w << 16); }
; DI float bfhi(unsigned w) { return __uint_as_float(w & 0xffff0000u); }
; DI u32x4 pack8(f32x4 v0, f32x4 v1) { u32x4 w; w.x = cvtpk(v0[0], v0[1]); w.y = cvtpk(v0[2], v0[3]); w.z = cvtpk(v1[0], v1[1]); w.w = cvtpk(v1[2], v1[3]); return w; }
;     DI void operator()(const f32x4 (&acc)[2][2][4][2], const Unit& u, int wr, int wc, int fr, int fq) const {
;     ...
;             for (int ai = 0; ai < 2; ++ai)
; #pragma unroll
;                 for (int m = 0; m < 4; ++m) { const int row = row0 + ai * HALF + m * 16; bf16_t* rowp = O + (size_t)row * DM + col0;
;                     const bf16_t* gp = Z + (size_t)row * LDZ + ZC_G + u.seg * DM + col0;
; #pragma unroll
;                     for (int bj = 0; bj < 2; ++bj) { const u32x4 gw = *(const u32x4*)(gp + bj * HALF);
;                         f32x4 v0 = acc[ai][bj][m][0], v1 = acc[ai][bj][m][1];
;                         v0[0] *= bflo(gw.x); v0[1] *= bfhi(gw.x); v0[2] *= bflo(gw.y); v0[3] *= bfhi(gw.y);
;                         v1[0] *= bflo(gw.z); v1[1] *= bfhi(gw.z); v1[2] *= bflo(gw.w); v1[3] *= bfhi(gw.w);
;                         if (u.seg > 0) { const u32x4 pw = *(const u32x4*)(rowp + bj * HALF);
;                             v0[0] += bflo(pw.x); v0[1] += bfhi(pw.x); v0[2] += bflo(pw.y); v0[3] += bfhi(pw.y);
;                             v1[0] += bflo(pw.z); v1[1] += bfhi(pw.z); v1[2] += bflo(pw.w); v1[3] += bfhi(pw.w); }
;                         *(u32x4*)(rowp + bj * HALF) = pack8(v0, v1); } }
.Lepi2_go_3:
	s_waitcnt vmcnt(0)
	v_lshlrev_b32_e32 v147, 16, v160
	v_and_b32_e32 v148, 0xffff0000, v160
	v_lshlrev_b32_e32 v149, 16, v161
	v_and_b32_e32 v150, 0xffff0000, v161
	v_lshlrev_b32_e32 v151, 16, v162
	v_and_b32_e32 v152, 0xffff0000, v162
	v_lshlrev_b32_e32 v153, 16, v163
	v_and_b32_e32 v154, 0xffff0000, v163
	v_mul_f32_e32 v30, v30, v147
	v_mul_f32_e32 v31, v31, v148
	v_mul_f32_e32 v32, v32, v149
	v_mul_f32_e32 v33, v33, v150
	v_mul_f32_e32 v26, v26, v151
	v_mul_f32_e32 v27, v27, v152
	v_mul_f32_e32 v28, v28, v153
	v_mul_f32_e32 v29, v29, v154
	v_lshlrev_b32_e32 v147, 16, v194
	v_and_b32_e32 v148, 0xffff0000, v194
	v_lshlrev_b32_e32 v149, 16, v195
	v_and_b32_e32 v150, 0xffff0000, v195
	v_lshlrev_b32_e32 v151, 16, v196
	v_and_b32_e32 v152, 0xffff0000, v196
	v_lshlrev_b32_e32 v153, 16, v197
	v_and_b32_e32 v154, 0xffff0000, v197
	v_add_f32_e32 v30, v30, v147
	v_add_f32_e32 v31, v31, v148
	v_add_f32_e32 v32, v32, v149
	v_add_f32_e32 v33, v33, v150
	v_add_f32_e32 v26, v26, v151
	v_add_f32_e32 v27, v27, v152
	v_add_f32_e32 v28, v28, v153
	v_add_f32_e32 v29, v29, v154
	v_cvt_pk_bf16_f32 v234, v30, v31
	v_cvt_pk_bf16_f32 v235, v32, v33
	v_cvt_pk_bf16_f32 v236, v26, v27
	v_cvt_pk_bf16_f32 v237, v28, v29
	global_store_dwordx4 v206, v[234:237], s[56:57]
	v_lshlrev_b32_e32 v147, 16, v164
	v_and_b32_e32 v148, 0xffff0000, v164
	v_lshlrev_b32_e32 v149, 16, v165
	v_and_b32_e32 v150, 0xffff0000, v165
	v_lshlrev_b32_e32 v151, 16, v166
	v_and_b32_e32 v152, 0xffff0000, v166
	v_lshlrev_b32_e32 v153, 16, v167
	v_and_b32_e32 v154, 0xffff0000, v167
	v_mul_f32_e32 v22, v22, v147
	v_mul_f32_e32 v23, v23, v148
	v_mul_f32_e32 v24, v24, v149
	v_mul_f32_e32 v25, v25, v150
	v_mul_f32_e32 v18, v18, v151
	v_mul_f32_e32 v19, v19, v152
	v_mul_f32_e32 v20, v20, v153
	v_mul_f32_e32 v21, v21, v154
	v_lshlrev_b32_e32 v147, 16, v198
	v_and_b32_e32 v148, 0xffff0000, v198
	v_lshlrev_b32_e32 v149, 16, v199
	v_and_b32_e32 v150, 0xffff0000, v199
	v_lshlrev_b32_e32 v151, 16, v200
	v_and_b32_e32 v152, 0xffff0000, v200
	v_lshlrev_b32_e32 v153, 16, v201
	v_and_b32_e32 v154, 0xffff0000, v201
	v_add_f32_e32 v22, v22, v147
	v_add_f32_e32 v23, v23, v148
	v_add_f32_e32 v24, v24, v149
	v_add_f32_e32 v25, v25, v150
	v_add_f32_e32 v18, v18, v151
	v_add_f32_e32 v19, v19, v152
	v_add_f32_e32 v20, v20, v153
	v_add_f32_e32 v21, v21, v154
	v_cvt_pk_bf16_f32 v238, v22, v23
	v_cvt_pk_bf16_f32 v239, v24, v25
	v_cvt_pk_bf16_f32 v240, v18, v19
	v_cvt_pk_bf16_f32 v241, v20, v21
	global_store_dwordx4 v206, v[238:241], s[56:57] offset:256
	v_lshlrev_b32_e32 v147, 16, v168
	v_and_b32_e32 v148, 0xffff0000, v168
	v_lshlrev_b32_e32 v149, 16, v169
	v_and_b32_e32 v150, 0xffff0000, v169
	v_lshlrev_b32_e32 v151, 16, v170
	v_and_b32_e32 v152, 0xffff0000, v170
	v_lshlrev_b32_e32 v153, 16, v171
	v_and_b32_e32 v154, 0xffff0000, v171
	v_mul_f32_e32 v14, v14, v147
	v_mul_f32_e32 v15, v15, v148
	v_mul_f32_e32 v16, v16, v149
	v_mul_f32_e32 v17, v17, v150
	v_mul_f32_e32 v10, v10, v151
	v_mul_f32_e32 v11, v11, v152
	v_mul_f32_e32 v12, v12, v153
	v_mul_f32_e32 v13, v13, v154
	v_lshlrev_b32_e32 v147, 16, v202
	v_and_b32_e32 v148, 0xffff0000, v202
	v_lshlrev_b32_e32 v149, 16, v203
	v_and_b32_e32 v150, 0xffff0000, v203
	v_lshlrev_b32_e32 v151, 16, v204
	v_and_b32_e32 v152, 0xffff0000, v204
	v_lshlrev_b32_e32 v153, 16, v205
	v_and_b32_e32 v154, 0xffff0000, v205
	v_add_f32_e32 v14, v14, v147
	v_add_f32_e32 v15, v15, v148
	v_add_f32_e32 v16, v16, v149
	v_add_f32_e32 v17, v17, v150
	v_add_f32_e32 v10, v10, v151
	v_add_f32_e32 v11, v11, v152
	v_add_f32_e32 v12, v12, v153
	v_add_f32_e32 v13, v13, v154
	v_cvt_pk_bf16_f32 v234, v14, v15
	v_cvt_pk_bf16_f32 v235, v16, v17
	v_cvt_pk_bf16_f32 v236, v10, v11
	v_cvt_pk_bf16_f32 v237, v12, v13
	global_store_dwordx4 v207, v[234:237], s[56:57]
	v_lshlrev_b32_e32 v147, 16, v172
	v_and_b32_e32 v148, 0xffff0000, v172
	v_lshlrev_b32_e32 v149, 16, v173
	v_and_b32_e32 v150, 0xffff0000, v173
	v_lshlrev_b32_e32 v151, 16, v174
	v_and_b32_e32 v152, 0xffff0000, v174
	v_lshlrev_b32_e32 v153, 16, v175
	v_and_b32_e32 v154, 0xffff0000, v175
	v_mul_f32_e32 v6, v6, v147
	v_mul_f32_e32 v7, v7, v148
	v_mul_f32_e32 v8, v8, v149
	v_mul_f32_e32 v9, v9, v150
	v_mul_f32_e32 v2, v2, v151
	v_mul_f32_e32 v3, v3, v152
	v_mul_f32_e32 v4, v4, v153
	v_mul_f32_e32 v5, v5, v154
	v_lshlrev_b32_e32 v147, 16, v176
	v_and_b32_e32 v148, 0xffff0000, v176
	v_lshlrev_b32_e32 v149, 16, v177
	v_and_b32_e32 v150, 0xffff0000, v177
	v_lshlrev_b32_e32 v151, 16, v178
	v_and_b32_e32 v152, 0xffff0000, v178
	v_lshlrev_b32_e32 v153, 16, v179
	v_and_b32_e32 v154, 0xffff0000, v179
	v_add_f32_e32 v6, v6, v147
	v_add_f32_e32 v7, v7, v148
	v_add_f32_e32 v8, v8, v149
	v_add_f32_e32 v9, v9, v150
	v_add_f32_e32 v2, v2, v151
	v_add_f32_e32 v3, v3, v152
	v_add_f32_e32 v4, v4, v153
	v_add_f32_e32 v5, v5, v154
	v_cvt_pk_bf16_f32 v238, v6, v7
	v_cvt_pk_bf16_f32 v239, v8, v9
	v_cvt_pk_bf16_f32 v240, v2, v3
	v_cvt_pk_bf16_f32 v241, v4, v5
	global_store_dwordx4 v207, v[238:241], s[56:57] offset:256
	s_mov_b64 s[0:1], 0

; #define DMA(buf, k0) do { _Pragma("unroll") for (int _i = 0; _i < NI; ++_i) { \
;         char* _d = (_i < 2) ? V_lds + (buf) * SHM_V + (wu + 8 * _i) * 1024 : K_lds + (buf) * SHM_K + (wu + 8 * _i - 16) * 1024; \
;         __builtin_amdgcn_global_load_lds((const unsigned*)(sp[_i] + (size_t)(k0) * sld[_i]), (LAS unsigned*)_d, 16, 0, 0); } } while (0)
; template <int DQK, int MODE>
; DI void attn_body(const AttnArgs& a, char* lds) {
;     ...
;     DMA(0, 0); asm volatile("s_waitcnt vmcnt(0)" ::: "memory"); __syncthreads();
;     if (wid >= 4) __builtin_amdgcn_s_setprio(1);
; #pragma unroll 1
;     for (int j = 0; j < NT; ++j) {
;         const int cur = j & 1;
;         if (j + 1 < NT) DMA(cur ^ 1, (j + 1) * 64);
.Lprio_skip_1:
	s_or_b64 exec, exec, s[66:67]
	v_mov_b32_e32 v196, 0
	v_mov_b32_e32 v197, 0
	v_mov_b32_e32 v198, 0
	v_mov_b32_e32 v199, 0
	v_mov_b32_e32 v200, 0
	v_mov_b32_e32 v201, 0
	v_mov_b32_e32 v202, 0
	v_mov_b32_e32 v203, 0
	v_mov_b32_e32 v204, 0
	v_mov_b32_e32 v205, 0
	v_mov_b32_e32 v206, 0
	v_mov_b32_e32 v207, 0
	v_mov_b32_e32 v208, 0
	v_mov_b32_e32 v209, 0
	v_mov_b32_e32 v210, 0
	v_mov_b32_e32 v211, 0
	v_subrev_u32_e32 v235, s12, v150
	v_subrev_u32_e32 v236, s12, v152
	v_subrev_u32_e32 v237, s12, v154
	v_add_u32_e32 v237, 0x800, v237
	s_add_u32 s89, s12, 0x170000
	s_addc_u32 s90, s14, 0
	v_mov_b32_e32 v238, s19
	s_mov_b32 s94, 2
	ds_read_b32 v239, v238 offset:1024
	ds_read_b32 v238, v238
	s_waitcnt lgkmcnt(0)
	s_cmp_lt_u32 s16, 0x1000
	s_cbranch_scc0 .Lstg_a_pro
	s_barrier

; #define SBAR() __builtin_amdgcn_sched_barrier(0)
; template <int I, int N, class F> DI void cfor(F&& f) { if constexpr (I < N) { f(std::integral_constant<int, I>{}); cfor<I + 1, N>(f); } }
; template <int OFF> DI void dsr128(bf16x8& r, int addr) { asm volatile("ds_read_b128 %0, %1 offset:%2" : "=&v"(r) : "v"(addr), "i"(OFF) : "memory"); }
; template <int N> DI void wait_lgkm() { asm volatile("s_waitcnt lgkmcnt(%0)" :: "i"(N) : "memory"); }
; template <int DQK, int MODE>
; DI void attn_body(const AttnArgs& a, char* lds) {
;     ...
;     auto qkt = [&](f32x16& p0, f32x16& p1, const int kofs) {
;         p0 = f32x16{}; p1 = f32x16{};
;         int kc[NB];
; #pragma unroll
;         for (int i = 0; i < NB; ++i) kc[i] = kb[i] + kofs;
;         bf16x8 fk[2][2]; bf16x8 fq[2];
;         auto rd = [&](auto ic) { constexpr int d0 = decltype(ic)::value; constexpr int sl = d0 & 1;
;             dsr128<(d0 / NB) * (NB * 32)>(fk[sl][0], kc[d0 % NB]); dsr128<(d0 / NB) * (NB * 32) + 32 * KROWB>(fk[sl][1], kc[d0 % NB]);
;             if constexpr (MODE == 2 && d0 >= NQR) dsr128<(d0 - NQR) * 1024>(fq[sl], qra); };
;         rd(std::integral_constant<int, 0>{});
;         cfor<0, ND0>([&](auto ic) { constexpr int d0 = decltype(ic)::value; constexpr int sl = d0 & 1;
;             if constexpr (d0 + 1 < ND0) { rd(std::integral_constant<int, d0 + 1>{}); wait_lgkm<(MODE == 2 && d0 + 1 >= NQR) ? 3 : 2>(); }
;             else wait_lgkm<0>();
;             SBAR();
;             bf16x8 qf; if constexpr (MODE == 2 && d0 >= NQR) qf = fq[sl]; else qf = qr[d0 < NQR ? d0 : 0];
;             p0 = __builtin_amdgcn_mfma_f32_32x32x16_bf16(fk[sl][0], qf, p0, 0, 0, 0);
;             p1 = __builtin_amdgcn_mfma_f32_32x32x16_bf16(fk[sl][1], qf, p1, 0, 0, 0); });
;     };
;     ...
;             } else {
;                 const int base = k0 - (qw0 + r32) + 4 * hi + 128;
; #pragma unroll
;                 for (int r = 0; r < 16; ++r) { const int i0 = base + (r & 3) + 8 * (r >> 2);
;                     const int j0 = min(max(i0, 0), 256), j1 = min(max(i0 + 32, 0), 256);
;                     p0[r] = fmaf(p0[r], C, a.tab[j0]); p1[r] = fmaf(p1[r], C, a.tab[j1]); }
.LBB0_744:
	v_add_u32_e32 v70, s37, v170
	ds_read_b128 v[66:69], v70 offset:0
	ds_read_b128 v[82:85], v70 offset:0x1000
	v_add_u32_e32 v71, s37, v171
	ds_read_b128 v[98:101], v71 offset:0
	ds_read_b128 v[102:105], v71 offset:0x1000
	s_waitcnt lgkmcnt(2)
	v_add_u32_e32 v114, s37, v172
	v_add_u32_e32 v115, s37, v173
	v_mfma_f32_32x32x16_bf16 v[66:81], v[66:69], v[130:133], v[196:211]
	ds_read_b128 v[106:109], v114 offset:0
	ds_read_b128 v[110:113], v114 offset:0x1000
	s_waitcnt lgkmcnt(2)
	v_mfma_f32_32x32x16_bf16 v[82:97], v[82:85], v[130:133], v[196:211]
	v_mfma_f32_32x32x16_bf16 v[66:81], v[98:101], v[134:137], v[66:81]
	ds_read_b128 v[98:101], v115 offset:0
	v_mfma_f32_32x32x16_bf16 v[82:97], v[102:105], v[134:137], v[82:97]
	ds_read_b128 v[102:105], v115 offset:0x1000
	s_waitcnt lgkmcnt(2)
	v_mfma_f32_32x32x16_bf16 v[66:81], v[106:109], v[138:141], v[66:81]
	s_waitcnt lgkmcnt(0)
	v_mfma_f32_32x32x16_bf16 v[82:97], v[110:113], v[138:141], v[82:97]
	v_mfma_f32_32x32x16_bf16 v[66:81], v[98:101], v[142:145], v[66:81]
	v_add_u32_e32 v194, s35, v176
	v_add_u32_e32 v98, 0xffffff21, v194
	s_movk_i32 s37, 0xfea2
	v_cmp_lt_u32_e32 vcc, s37, v98
	v_mfma_f32_32x32x16_bf16 v[82:97], v[102:105], v[142:145], v[82:97]
	s_and_saveexec_b64 s[50:51], vcc
	s_xor_b64 s[68:69], exec, s[50:51]
	s_cbranch_execz .LBB0_746
	s_mov_b32 s94, 2
	s_mov_b32 s32, 1
	v_add_u32_e32 v122, s35, v175
	v_add_u32_e32 v98, 64, v122
	v_med3_i32 v99, v98, 0, v191
	v_max_i32_e32 v98, 0xffffffe0, v98
	v_add_u32_e32 v98, 32, v98
	v_min_u32_e32 v98, 0x100, v98
	v_lshl_add_u32 v100, v98, 2, s19
	v_add_u32_e32 v98, 0x41, v122
	v_med3_i32 v101, v98, 0, v191
	v_max_i32_e32 v98, 0xffffffe0, v98
	v_add_u32_e32 v98, 32, v98
	v_min_u32_e32 v98, 0x100, v98
	v_lshl_add_u32 v102, v98, 2, s19
	v_add_u32_e32 v98, 0x42, v122
	v_med3_i32 v103, v98, 0, v191
	v_max_i32_e32 v98, 0xffffffe0, v98
	v_add_u32_e32 v98, 32, v98
	v_min_u32_e32 v98, 0x100, v98
	v_lshl_add_u32 v104, v98, 2, s19
	v_add_u32_e32 v98, 0x43, v122
	v_med3_i32 v105, v98, 0, v191
	v_max_i32_e32 v98, 0xffffffe0, v98
	v_add_u32_e32 v98, 32, v98
	v_min_u32_e32 v98, 0x100, v98
	v_lshl_add_u32 v99, v99, 2, s19
	v_lshl_add_u32 v101, v101, 2, s19
	v_lshl_add_u32 v103, v103, 2, s19
	v_lshl_add_u32 v105, v105, 2, s19
	v_lshl_add_u32 v106, v98, 2, s19
	ds_read_b32 v98, v99
	ds_read_b32 v100, v100
	ds_read_b32 v99, v101
	ds_read_b32 v101, v102
	ds_read_b32 v102, v103
	ds_read_b32 v104, v104
	ds_read_b32 v103, v105
	ds_read_b32 v105, v106
	v_add_u32_e32 v106, 0x48, v122
	v_med3_i32 v107, v106, 0, v191
	v_max_i32_e32 v106, 0xffffffe0, v106
	v_add_u32_e32 v106, 32, v106
	v_min_u32_e32 v106, 0x100, v106
	v_lshl_add_u32 v108, v106, 2, s19
	v_add_u32_e32 v106, 0x49, v122
	v_med3_i32 v109, v106, 0, v191
	v_max_i32_e32 v106, 0xffffffe0, v106
	v_add_u32_e32 v106, 32, v106
	v_min_u32_e32 v106, 0x100, v106
	v_lshl_add_u32 v110, v106, 2, s19
	v_add_u32_e32 v106, 0x4a, v122
	v_med3_i32 v111, v106, 0, v191
	v_max_i32_e32 v106, 0xffffffe0, v106
	v_add_u32_e32 v106, 32, v106
	v_min_u32_e32 v106, 0x100, v106
	v_lshl_add_u32 v112, v106, 2, s19
	v_add_u32_e32 v106, 0x4b, v122
	v_med3_i32 v113, v106, 0, v191
	v_max_i32_e32 v106, 0xffffffe0, v106
	v_add_u32_e32 v106, 32, v106
	v_min_u32_e32 v106, 0x100, v106
	v_lshl_add_u32 v107, v107, 2, s19
	v_lshl_add_u32 v109, v109, 2, s19
	v_lshl_add_u32 v111, v111, 2, s19
	v_lshl_add_u32 v113, v113, 2, s19
	v_lshl_add_u32 v114, v106, 2, s19
	ds_read_b32 v106, v107
	ds_read_b32 v108, v108
	ds_read_b32 v107, v109
	ds_read_b32 v109, v110
	ds_read_b32 v110, v111
	ds_read_b32 v112, v112
	ds_read_b32 v111, v113
	ds_read_b32 v113, v114
	v_add_u32_e32 v114, 0x50, v122
	v_med3_i32 v115, v114, 0, v191
	v_max_i32_e32 v114, 0xffffffe0, v114
	v_add_u32_e32 v114, 32, v114
	v_min_u32_e32 v114, 0x100, v114
	v_lshl_add_u32 v116, v114, 2, s19
	v_add_u32_e32 v114, 0x51, v122
	v_med3_i32 v117, v114, 0, v191
	v_max_i32_e32 v114, 0xffffffe0, v114
	v_add_u32_e32 v114, 32, v114
	v_min_u32_e32 v114, 0x100, v114
	v_lshl_add_u32 v118, v114, 2, s19
	v_add_u32_e32 v114, 0x52, v122
	v_med3_i32 v119, v114, 0, v191
	v_max_i32_e32 v114, 0xffffffe0, v114
	v_add_u32_e32 v114, 32, v114
	v_min_u32_e32 v114, 0x100, v114
	v_lshl_add_u32 v120, v114, 2, s19
	v_add_u32_e32 v114, 0x53, v122
	v_med3_i32 v121, v114, 0, v191
	v_max_i32_e32 v114, 0xffffffe0, v114
	v_add_u32_e32 v114, 32, v114
	v_min_u32_e32 v114, 0x100, v114
	v_lshl_add_u32 v115, v115, 2, s19
	v_lshl_add_u32 v117, v117, 2, s19
	v_lshl_add_u32 v119, v119, 2, s19
	v_lshl_add_u32 v121, v121, 2, s19
	v_lshl_add_u32 v123, v114, 2, s19
	ds_read_b32 v114, v115
	ds_read_b32 v116, v116
	ds_read_b32 v115, v117
	ds_read_b32 v117, v118
	ds_read_b32 v118, v119
	ds_read_b32 v120, v120
	ds_read_b32 v119, v121
	ds_read_b32 v121, v123
	v_add_u32_e32 v123, 0x58, v122
	v_add_u32_e32 v125, 0x59, v122
	v_add_u32_e32 v127, 0x5a, v122
	v_med3_i32 v124, v123, 0, v191
	v_max_i32_e32 v123, 0xffffffe0, v123
	v_med3_i32 v126, v125, 0, v191
	v_max_i32_e32 v125, 0xffffffe0, v125
	v_med3_i32 v128, v127, 0, v191
	v_max_i32_e32 v127, 0xffffffe0, v127
	v_add_u32_e32 v122, 0x5b, v122
	v_add_u32_e32 v123, 32, v123
	v_add_u32_e32 v125, 32, v125
	v_add_u32_e32 v127, 32, v127
	v_med3_i32 v129, v122, 0, v191
	v_max_i32_e32 v122, 0xffffffe0, v122
	s_waitcnt lgkmcnt(0)
; template <int DQK, int MODE>
; DI void attn_body(const AttnArgs& a, char* lds) {
;     ...
;     auto partialSM = [&](f32x16& p0, f32x16& p1, float& mn, float& alpha, int k0) {
;         if constexpr (MODE == 1) {
;             const int relmax = k0 + 63 - qw0, relmin = k0 - qw0 - 31;
;             if (relmax <= -128 || relmin >= 128) {
;                 const float bc = a.tab[relmax <= -128 ? 0 : 256];
;                 float pmax = p0[0];
; #pragma unroll
;                 for (int r = 1; r < 16; ++r) pmax = fmaxf(pmax, p0[r]);
; #pragma unroll
;                 for (int r = 0; r < 16; ++r) pmax = fmaxf(pmax, p1[r]);
;                 { auto rr = __builtin_amdgcn_permlane32_swap(__float_as_uint(pmax), __float_as_uint(pmax), false, false);
;                   pmax = fmaxf(__uint_as_float(rr[0]), __uint_as_float(rr[1])); }
;                 pmax = fmaf(pmax, C, bc);
;                 if (__builtin_expect(__all(pmax - m_reg <= THR_L2), 1)) { mn = m_reg; alpha = 1.f; }
;                 else { mn = fmaxf(m_reg, pmax); alpha = __builtin_amdgcn_exp2f(m_reg - mn); m_reg = mn; }
;     ...
;             } else {
;                 const int base = k0 - (qw0 + r32) + 4 * hi + 128;
; #pragma unroll
;                 for (int r = 0; r < 16; ++r) { const int i0 = base + (r & 3) + 8 * (r >> 2);
;                     const int j0 = min(max(i0, 0), 256), j1 = min(max(i0 + 32, 0), 256);
;                     p0[r] = fmaf(p0[r], C, a.tab[j0]); p1[r] = fmaf(p1[r], C, a.tab[j1]); }
;                 float pmax = p0[0];
; #pragma unroll
;                 for (int r = 1; r < 16; ++r) pmax = fmaxf(pmax, p0[r]);
; #pragma unroll
;                 for (int r = 0; r < 16; ++r) pmax = fmaxf(pmax, p1[r]);
;                 { auto rr = __builtin_amdgcn_permlane32_swap(__float_as_uint(pmax), __float_as_uint(pmax), false, false);
;                   pmax = fmaxf(__uint_as_float(rr[0]), __uint_as_float(rr[1])); }
;                 if (__builtin_expect(__all(pmax - m_reg <= THR_L2), 1)) { mn = m_reg; alpha = 1.f; }
;                 else { mn = fmaxf(m_reg, pmax); alpha = __builtin_amdgcn_exp2f(m_reg - mn); m_reg = mn; }
; #pragma unroll
;                 for (int r = 0; r < 16; ++r) { p0[r] -= mn; p1[r] -= mn; }
;             }
	v_sub_f32_e32 v66, v66, v196
	v_sub_f32_e32 v67, v67, v196
	v_sub_f32_e32 v68, v68, v196
	v_sub_f32_e32 v69, v69, v196
	v_sub_f32_e32 v70, v70, v196
	v_sub_f32_e32 v71, v71, v196
	v_sub_f32_e32 v72, v72, v196
	v_sub_f32_e32 v73, v73, v196
	v_sub_f32_e32 v74, v74, v196
	v_sub_f32_e32 v75, v75, v196
	v_sub_f32_e32 v76, v76, v196
	v_sub_f32_e32 v77, v77, v196
	v_sub_f32_e32 v78, v78, v196
	v_sub_f32_e32 v79, v79, v196
	v_sub_f32_e32 v80, v80, v196
	v_sub_f32_e32 v81, v81, v196
	v_sub_f32_e32 v82, v82, v196
	v_sub_f32_e32 v83, v83, v196
	v_sub_f32_e32 v84, v84, v196
	v_sub_f32_e32 v85, v85, v196
	v_sub_f32_e32 v86, v86, v196
	v_sub_f32_e32 v87, v87, v196
	v_sub_f32_e32 v88, v88, v196
	v_sub_f32_e32 v89, v89, v196
	v_sub_f32_e32 v90, v90, v196
	v_sub_f32_e32 v91, v91, v196
	v_sub_f32_e32 v92, v92, v196
	v_sub_f32_e32 v93, v93, v196
	v_sub_f32_e32 v94, v94, v196
	v_sub_f32_e32 v95, v95, v196
	v_sub_f32_e32 v96, v96, v196
	v_sub_f32_e32 v97, v97, v196
	v_pk_fma_f32 v[66:67], v[66:67], s[44:45], v[98:99] op_sel_hi:[1,0,1]
	v_min_u32_e32 v123, 0x100, v123
	v_min_u32_e32 v125, 0x100, v125
	v_min_u32_e32 v127, 0x100, v127
	v_add_u32_e32 v122, 32, v122
	v_max_f32_e32 v98, v66, v67
	v_pk_fma_f32 v[68:69], v[68:69], s[44:45], v[102:103] op_sel_hi:[1,0,1]
	v_lshl_add_u32 v124, v124, 2, s19
	v_lshl_add_u32 v123, v123, 2, s19
	v_lshl_add_u32 v126, v126, 2, s19
	v_lshl_add_u32 v125, v125, 2, s19
	v_lshl_add_u32 v128, v128, 2, s19
	v_lshl_add_u32 v127, v127, 2, s19
	v_min_u32_e32 v122, 0x100, v122
	v_lshl_add_u32 v129, v129, 2, s19
	v_max3_f32 v98, v98, v68, v69
	v_pk_fma_f32 v[70:71], v[70:71], s[44:45], v[106:107] op_sel_hi:[1,0,1]
	v_lshl_add_u32 v179, v122, 2, s19
	ds_read_b32 v122, v124
	ds_read_b32 v124, v123
	ds_read_b32 v123, v126
	ds_read_b32 v125, v125
	ds_read_b32 v126, v128
	ds_read_b32 v128, v127
	ds_read_b32 v127, v129
	ds_read_b32 v129, v179
	v_max3_f32 v98, v98, v70, v71
	v_pk_fma_f32 v[72:73], v[72:73], s[44:45], v[110:111] op_sel_hi:[1,0,1]
	v_pk_fma_f32 v[74:75], v[74:75], s[44:45], v[114:115] op_sel_hi:[1,0,1]
	v_max3_f32 v98, v98, v72, v73
	v_max3_f32 v98, v98, v74, v75
	v_pk_fma_f32 v[76:77], v[76:77], s[44:45], v[118:119] op_sel_hi:[1,0,1]
	s_waitcnt lgkmcnt(0)
	v_pk_fma_f32 v[78:79], v[78:79], s[44:45], v[122:123] op_sel_hi:[1,0,1]
	v_max3_f32 v98, v98, v76, v77
	v_max3_f32 v98, v98, v78, v79
	v_pk_fma_f32 v[80:81], v[80:81], s[44:45], v[126:127] op_sel_hi:[1,0,1]
	v_pk_fma_f32 v[82:83], v[82:83], s[44:45], v[100:101] op_sel_hi:[1,0,1]
	v_max3_f32 v98, v98, v80, v81
	v_pk_fma_f32 v[84:85], v[84:85], s[44:45], v[104:105] op_sel_hi:[1,0,1]
	v_max3_f32 v98, v98, v82, v83
	v_pk_fma_f32 v[86:87], v[86:87], s[44:45], v[108:109] op_sel_hi:[1,0,1]
	v_max3_f32 v98, v98, v84, v85
	v_pk_fma_f32 v[88:89], v[88:89], s[44:45], v[112:113] op_sel_hi:[1,0,1]
	v_max3_f32 v98, v98, v86, v87
	v_pk_fma_f32 v[90:91], v[90:91], s[44:45], v[116:117] op_sel_hi:[1,0,1]
	v_max3_f32 v98, v98, v88, v89
	v_pk_fma_f32 v[92:93], v[92:93], s[44:45], v[120:121] op_sel_hi:[1,0,1]
	v_max3_f32 v98, v98, v90, v91
	v_pk_fma_f32 v[94:95], v[94:95], s[44:45], v[124:125] op_sel_hi:[1,0,1]
	v_max3_f32 v98, v98, v92, v93
	v_pk_fma_f32 v[96:97], v[96:97], s[44:45], v[128:129] op_sel_hi:[1,0,1]
	v_max3_f32 v98, v98, v94, v95
	v_max3_f32 v98, v98, v96, v97
	v_mov_b32_e32 v99, v98
	s_nop 1
	v_permlane32_swap_b32_e32 v98, v99
	v_max_f32_e32 v99, v99, v99
	v_max_f32_e32 v98, v98, v98
	v_max_f32_e32 v98, v98, v99
	v_sub_f32_e32 v99, v98, v177
	v_cmp_ge_f32_e32 vcc, s97, v99
	v_max_f32_e32 v99, v177, v177
	v_max_f32_e32 v98, v99, v98
	v_sub_f32_e32 v99, v177, v98
	v_exp_f32_e32 v99, v99
	s_cmp_eq_u64 vcc, exec
	s_cselect_b64 vcc, -1, 0
	v_cndmask_b32_e32 v177, v98, v177, vcc
	v_cndmask_b32_e64 v179, v99, 1.0, vcc
	v_sub_f32_e32 v81, v81, v177
	v_sub_f32_e32 v80, v80, v177
	v_sub_f32_e32 v79, v79, v177
	v_sub_f32_e32 v78, v78, v177
	v_sub_f32_e32 v77, v77, v177
	v_sub_f32_e32 v76, v76, v177
	v_sub_f32_e32 v75, v75, v177
	v_sub_f32_e32 v74, v74, v177
	v_sub_f32_e32 v73, v73, v177
	v_sub_f32_e32 v72, v72, v177
	v_sub_f32_e32 v71, v71, v177
	v_sub_f32_e32 v70, v70, v177
	v_sub_f32_e32 v69, v69, v177
	v_sub_f32_e32 v68, v68, v177
	v_sub_f32_e32 v67, v67, v177
	v_sub_f32_e32 v66, v66, v177
	v_sub_f32_e32 v97, v97, v177
	v_sub_f32_e32 v96, v96, v177
	v_sub_f32_e32 v95, v95, v177
	v_sub_f32_e32 v94, v94, v177
	v_sub_f32_e32 v93, v93, v177
	v_sub_f32_e32 v92, v92, v177
	v_sub_f32_e32 v91, v91, v177
	v_sub_f32_e32 v90, v90, v177
	v_sub_f32_e32 v89, v89, v177
	v_sub_f32_e32 v88, v88, v177
	v_sub_f32_e32 v87, v87, v177
	v_sub_f32_e32 v86, v86, v177
	v_sub_f32_e32 v85, v85, v177
	v_sub_f32_e32 v84, v84, v177
	v_sub_f32_e32 v83, v83, v177
	v_sub_f32_e32 v82, v82, v177
.LBB0_746:
	s_andn2_saveexec_b64 s[68:69], s[68:69]
	s_cbranch_execz .LBB0_748
	s_nop 1
	v_max_f32_e32 v99, v66, v67
	v_max3_f32 v99, v99, v68, v69
	v_max3_f32 v99, v99, v70, v71
	v_max3_f32 v99, v99, v72, v73
	v_max3_f32 v99, v99, v74, v75
	v_max3_f32 v99, v99, v76, v77
	v_max3_f32 v99, v99, v78, v79
	v_max3_f32 v99, v99, v80, v81
	v_max3_f32 v99, v99, v82, v83
	v_max3_f32 v99, v99, v84, v85
	v_max3_f32 v99, v99, v86, v87
	v_max3_f32 v99, v99, v88, v89
	v_max3_f32 v99, v99, v90, v91
	v_max3_f32 v99, v99, v92, v93
	v_max3_f32 v99, v99, v94, v95
	v_max3_f32 v99, v99, v96, v97
	v_mov_b32_e32 v100, v99
	s_add_i32 s37, s35, s93
	s_cmp_lt_i32 s37, 0xffffff82
	s_cselect_b32 s37, 0, 1
	v_permlane32_swap_b32_e32 v99, v100
	v_max_f32_e32 v99, v99, v100
	s_cmp_lg_u32 s37, s94
	s_cbranch_scc1 .Lfar_a_slow
	v_cmp_ge_f32_e32 vcc, s97, v99
	s_mov_b32 s32, 0
	s_cmp_eq_u64 vcc, exec
	s_cbranch_scc1 .Lfar_a_fast
; template <int DQK, int MODE>
; DI void attn_body(const AttnArgs& a, char* lds) {
;     ...
;                 { auto rr = __builtin_amdgcn_permlane32_swap(__float_as_uint(pmax), __float_as_uint(pmax), false, false);
;                   pmax = fmaxf(__uint_as_float(rr[0]), __uint_as_float(rr[1])); }
;                 pmax = fmaf(pmax, C, bc);
;                 if (__builtin_expect(__all(pmax - m_reg <= THR_L2), 1)) { mn = m_reg; alpha = 1.f; }
;                 else { mn = fmaxf(m_reg, pmax); alpha = __builtin_amdgcn_exp2f(m_reg - mn); m_reg = mn; }
;                 const float off = bc - mn;
; #pragma unroll
;                 for (int r = 0; r < 16; ++r) { p0[r] = fmaf(p0[r], C, off); p1[r] = fmaf(p1[r], C, off); }
;     ...
;     auto finishSM = [&](f32x16& p0, f32x16& p1, float alpha, bf16x8& pa0, bf16x8& pa1, bf16x8& pa2, bf16x8& pa3) {
; #pragma unroll
;         for (int r = 0; r < 16; ++r) p1[r] = __builtin_amdgcn_exp2f(p1[r]);
;         float ps = 0;
; #pragma unroll
;         for (int r = 0; r < 16; ++r) ps += p0[r];
; #pragma unroll
;         for (int r = 0; r < 16; ++r) ps += p1[r];
;         { auto rr = __builtin_amdgcn_permlane32_swap(__float_as_uint(ps), __float_as_uint(ps), false, false);
;           ps = __uint_as_float(rr[0]) + __uint_as_float(rr[1]); }
;         l_reg = l_reg * alpha + ps;
;     ...
;         PK4(p0, 0, pa0); PK4(p0, 8, pa1); PK4(p1, 0, pa2); PK4(p1, 8, pa3);
.Lfar_a_slow:
	s_mov_b32 s94, s37
	s_cmp_eq_u32 s37, 0
	s_cselect_b64 vcc, -1, 0
	v_cndmask_b32_e32 v241, v239, v238, vcc
	v_sub_f32_e32 v99, v99, v196
	v_add_f32_e32 v99, v99, v241
	v_max_f32_e32 v100, v177, v99
	v_sub_f32_e32 v99, v177, v100
	v_exp_f32_e32 v179, v99
	v_mov_b32_e32 v177, v100
	v_sub_f32_e32 v99, v241, v177
	v_sub_f32_e32 v100, v99, v196
	v_add_f32_e32 v66, v66, v100
	v_add_f32_e32 v67, v67, v100
	v_add_f32_e32 v68, v68, v100
	v_add_f32_e32 v69, v69, v100
	v_add_f32_e32 v70, v70, v100
	v_add_f32_e32 v71, v71, v100
	v_add_f32_e32 v72, v72, v100
	v_add_f32_e32 v73, v73, v100
	v_add_f32_e32 v74, v74, v100
	v_add_f32_e32 v75, v75, v100
	v_add_f32_e32 v76, v76, v100
	v_add_f32_e32 v77, v77, v100
	v_add_f32_e32 v78, v78, v100
	v_add_f32_e32 v79, v79, v100
	v_add_f32_e32 v80, v80, v100
	v_add_f32_e32 v81, v81, v100
	v_add_f32_e32 v82, v82, v100
	v_add_f32_e32 v83, v83, v100
	v_add_f32_e32 v84, v84, v100
	v_add_f32_e32 v85, v85, v100
	v_add_f32_e32 v86, v86, v100
	v_add_f32_e32 v87, v87, v100
	v_add_f32_e32 v88, v88, v100
	v_add_f32_e32 v89, v89, v100
	v_add_f32_e32 v90, v90, v100
	v_add_f32_e32 v91, v91, v100
	v_add_f32_e32 v92, v92, v100
	v_add_f32_e32 v93, v93, v100
	v_add_f32_e32 v94, v94, v100
	v_add_f32_e32 v95, v95, v100
	v_add_f32_e32 v96, v96, v100
	v_add_f32_e32 v97, v97, v100
	v_mov_b32_e32 v196, v99
	v_mov_b32_e32 v197, v99
	v_mov_b32_e32 v198, v99
	v_mov_b32_e32 v199, v99
	v_mov_b32_e32 v200, v99
	v_mov_b32_e32 v201, v99
	v_mov_b32_e32 v202, v99
	v_mov_b32_e32 v203, v99
	v_mov_b32_e32 v204, v99
	v_mov_b32_e32 v205, v99
	v_mov_b32_e32 v206, v99
	v_mov_b32_e32 v207, v99
	v_mov_b32_e32 v208, v99
	v_mov_b32_e32 v209, v99
	v_mov_b32_e32 v210, v99
	v_mov_b32_e32 v211, v99
	s_mov_b32 s32, 1
.Lfar_a_fast:
.LBB0_748:
	s_or_b64 exec, exec, s[68:69]
	s_waitcnt vmcnt(0)
	s_barrier
	s_cmp_lt_u32 s17, s22
	s_cbranch_scc0 .Lstg_a_nov
	s_lshl_b32 s46, s36, 14
	s_xor_b32 s46, s46, 0x4000
	s_add_i32 s46, s16, s46
	s_mov_b32 s50, s89
	s_mov_b32 s51, s90
	s_mov_b32 m0, s46
	s_nop 0
	global_load_lds_dwordx4 v235, s[50:51]
	s_add_i32 m0, s46, 0x2000
	s_nop 0
	global_load_lds_dwordx4 v236, s[50:51]
.Lstg_a_nov:
	s_nop 0
	v_exp_f32_e32 v66, v66
	v_exp_f32_e32 v67, v67
	v_exp_f32_e32 v68, v68
	v_add_f32_e32 v232, v66, v67
	v_exp_f32_e32 v69, v69
	v_add_f32_e32 v232, v232, v68
	v_exp_f32_e32 v70, v70
	v_add_f32_e32 v232, v232, v69
	v_exp_f32_e32 v71, v71
	v_add_f32_e32 v232, v232, v70
	v_exp_f32_e32 v72, v72
	v_add_f32_e32 v232, v232, v71
	v_exp_f32_e32 v73, v73
	v_add_f32_e32 v232, v232, v72
	v_exp_f32_e32 v74, v74
	v_add_f32_e32 v232, v232, v73
	v_exp_f32_e32 v75, v75
	v_add_f32_e32 v232, v232, v74
	v_exp_f32_e32 v76, v76
	v_add_f32_e32 v232, v232, v75
	v_exp_f32_e32 v77, v77
	v_add_f32_e32 v232, v232, v76
	v_exp_f32_e32 v78, v78
	v_add_f32_e32 v232, v232, v77
	v_exp_f32_e32 v79, v79
	v_add_f32_e32 v232, v232, v78
	v_exp_f32_e32 v80, v80
	v_add_f32_e32 v232, v232, v79
	v_exp_f32_e32 v81, v81
	v_add_f32_e32 v232, v232, v80
	v_exp_f32_e32 v82, v82
	v_add_f32_e32 v232, v232, v81
	v_exp_f32_e32 v83, v83
	v_add_f32_e32 v232, v232, v82
	v_exp_f32_e32 v84, v84
	v_add_f32_e32 v232, v232, v83
	v_exp_f32_e32 v85, v85
	v_add_f32_e32 v232, v232, v84
	v_exp_f32_e32 v86, v86
	v_add_f32_e32 v232, v232, v85
	v_exp_f32_e32 v87, v87
	v_add_f32_e32 v232, v232, v86
	v_exp_f32_e32 v88, v88
	v_add_f32_e32 v232, v232, v87
	v_exp_f32_e32 v89, v89
	v_add_f32_e32 v232, v232, v88
	v_exp_f32_e32 v90, v90
	v_add_f32_e32 v232, v232, v89
	v_exp_f32_e32 v91, v91
	v_add_f32_e32 v232, v232, v90
	v_exp_f32_e32 v92, v92
	v_add_f32_e32 v232, v232, v91
	v_exp_f32_e32 v93, v93
	v_add_f32_e32 v232, v232, v92
	v_exp_f32_e32 v94, v94
	v_add_f32_e32 v232, v232, v93
	v_exp_f32_e32 v95, v95
	v_add_f32_e32 v232, v232, v94
	v_exp_f32_e32 v96, v96
	v_add_f32_e32 v232, v232, v95
	v_exp_f32_e32 v97, v97
	v_add_f32_e32 v232, v232, v96
	v_cvt_pk_bf16_f32 v212, v66, v67
	v_cvt_pk_bf16_f32 v213, v68, v69
	v_add_f32_e32 v232, v232, v97
	v_cvt_pk_bf16_f32 v214, v70, v71
	v_cvt_pk_bf16_f32 v215, v72, v73
	v_cvt_pk_bf16_f32 v216, v74, v75
	v_cvt_pk_bf16_f32 v217, v76, v77
	v_cvt_pk_bf16_f32 v218, v78, v79
	v_cvt_pk_bf16_f32 v219, v80, v81
	v_cvt_pk_bf16_f32 v220, v82, v83
	v_cvt_pk_bf16_f32 v221, v84, v85
	v_cvt_pk_bf16_f32 v222, v86, v87
	v_cvt_pk_bf16_f32 v223, v88, v89
	v_cvt_pk_bf16_f32 v224, v90, v91
	v_cvt_pk_bf16_f32 v225, v92, v93
	v_cvt_pk_bf16_f32 v226, v94, v95
	v_cvt_pk_bf16_f32 v227, v96, v97
	v_mov_b32_e32 v233, v232
	s_nop 1
	v_permlane32_swap_b32_e32 v232, v233
	s_cmp_eq_u32 s32, 0
	s_cbranch_scc1 .LBB0_752
	s_and_saveexec_b64 s[68:69], s[0:1]
	ds_write_b32 v169, v179 offset:128
	s_or_b64 exec, exec, s[68:69]
	s_waitcnt lgkmcnt(0)
	v_add_u32_e32 v96, v168, v0
	ds_read_b128 v[84:87], v96 offset:224
	ds_read_b128 v[88:91], v96 offset:192
	ds_read_b128 v[92:95], v96 offset:160
	ds_read_b128 v[96:99], v96 offset:128
	s_waitcnt lgkmcnt(0)
	v_pk_mul_f32 v[14:15], v[14:15], v[84:85]
	v_pk_mul_f32 v[10:11], v[10:11], v[88:89]
	v_pk_mul_f32 v[6:7], v[6:7], v[92:93]
	v_pk_mul_f32 v[16:17], v[16:17], v[86:87]
	v_pk_mul_f32 v[12:13], v[12:13], v[90:91]
	v_pk_mul_f32 v[8:9], v[8:9], v[94:95]
	v_pk_mul_f32 v[4:5], v[4:5], v[98:99]
	v_pk_mul_f32 v[2:3], v[2:3], v[96:97]
	v_pk_mul_f32 v[62:63], v[62:63], v[84:85]
	v_pk_mul_f32 v[58:59], v[58:59], v[88:89]
	v_pk_mul_f32 v[54:55], v[54:55], v[92:93]
	v_pk_mul_f32 v[64:65], v[64:65], v[86:87]
	v_pk_mul_f32 v[60:61], v[60:61], v[90:91]
	v_pk_mul_f32 v[56:57], v[56:57], v[94:95]
	v_pk_mul_f32 v[52:53], v[52:53], v[98:99]
	v_pk_mul_f32 v[50:51], v[50:51], v[96:97]
	v_pk_mul_f32 v[46:47], v[46:47], v[84:85]
	v_pk_mul_f32 v[42:43], v[42:43], v[88:89]
	v_pk_mul_f32 v[38:39], v[38:39], v[92:93]
	v_pk_mul_f32 v[48:49], v[48:49], v[86:87]
	v_pk_mul_f32 v[44:45], v[44:45], v[90:91]
	v_pk_mul_f32 v[40:41], v[40:41], v[94:95]
	v_pk_mul_f32 v[36:37], v[36:37], v[98:99]
	v_pk_mul_f32 v[34:35], v[34:35], v[96:97]
	v_pk_mul_f32 v[30:31], v[30:31], v[84:85]
	v_pk_mul_f32 v[26:27], v[26:27], v[88:89]
	v_pk_mul_f32 v[22:23], v[22:23], v[92:93]
	v_pk_mul_f32 v[32:33], v[32:33], v[86:87]
	v_pk_mul_f32 v[28:29], v[28:29], v[90:91]
	v_pk_mul_f32 v[24:25], v[24:25], v[94:95]
	v_pk_mul_f32 v[20:21], v[20:21], v[98:99]
	v_pk_mul_f32 v[18:19], v[18:19], v[96:97]
	v_mul_f32_e32 v178, v178, v179
; #define SBAR() __builtin_amdgcn_sched_barrier(0)
; template <int N> DI void wait_lgkm() { asm volatile("s_waitcnt lgkmcnt(%0)" :: "i"(N) : "memory"); }
; #define RESC(al) do { if (__any((al) < 1.f)) { if (hi == 0) al_l[r32] = (al); asm volatile("s_waitcnt lgkmcnt(0)" ::: "memory"); \
;     _Pragma("unroll") for (int d = 0; d < 4; ++d) _Pragma("unroll") for (int r = 0; r < 16; ++r) o[d][r] *= al_l[crow(r, hi)]; } } while (0)
; DI void pv_mm(f32x16* o, const s16x4* f, bf16x8 pa) {
;     ...
;     o[0] = __builtin_amdgcn_mfma_f32_32x32x16_bf16(pa, PK(f[0], f[1]), o[0], 0, 0, 0);
;     o[1] = __builtin_amdgcn_mfma_f32_32x32x16_bf16(pa, PK(f[2], f[3]), o[1], 0, 0, 0);
;     o[2] = __builtin_amdgcn_mfma_f32_32x32x16_bf16(pa, PK(f[4], f[5]), o[2], 0, 0, 0);
;     o[3] = __builtin_amdgcn_mfma_f32_32x32x16_bf16(pa, PK(f[6], f[7]), o[3], 0, 0, 0);
;     ...
; }
; DI void pv_d0(f32x16* o, int vb, bf16x8 pa0, bf16x8 pa1, bf16x8 pa2, bf16x8 pa3) {
;     s16x4 fa[8], fb[8];
;     v_rd8<0>(fa, vb);
;     v_rd8<1>(fb, vb); wait_lgkm<8>(); SBAR(); pv_mm(o, fa, pa0);
;     v_rd8<2>(fa, vb); wait_lgkm<8>(); SBAR(); pv_mm(o, fb, pa1);
;     v_rd8<3>(fb, vb); wait_lgkm<8>(); SBAR(); pv_mm(o, fa, pa2);
;     wait_lgkm<0>(); SBAR(); pv_mm(o, fb, pa3);
; }
; template <int DQK, int MODE>
; DI void attn_body(const AttnArgs& a, char* lds) {
;     ...
;         RESC(alpha);
;         pv_d0(o, vb0 + cur * SHM_V, pa0, pa1, pa2, pa3);
;         asm volatile("s_waitcnt vmcnt(0)" ::: "memory");
;         __syncthreads();
.LBB0_752:
	v_add_f32_e32 v82, v232, v233
	v_lshl_add_u32 v83, s36, 14, v174
	ds_read_b64_tr_b16 v[84:85], v83 offset:0
	ds_read_b64_tr_b16 v[86:87], v83 offset:0x800
	ds_read_b64_tr_b16 v[88:89], v83 offset:0x200
	ds_read_b64_tr_b16 v[90:91], v83 offset:0xa00
	ds_read_b64_tr_b16 v[92:93], v83 offset:0x400
	ds_read_b64_tr_b16 v[94:95], v83 offset:0xc00
	ds_read_b64_tr_b16 v[96:97], v83 offset:0x600
	ds_read_b64_tr_b16 v[98:99], v83 offset:0xe00
	ds_read_b64_tr_b16 v[100:101], v83 offset:0x1000
	ds_read_b64_tr_b16 v[102:103], v83 offset:0x1800
	ds_read_b64_tr_b16 v[104:105], v83 offset:0x1200
	ds_read_b64_tr_b16 v[106:107], v83 offset:0x1a00
	ds_read_b64_tr_b16 v[108:109], v83 offset:0x1400
	ds_read_b64_tr_b16 v[110:111], v83 offset:0x1c00
	ds_read_b64_tr_b16 v[112:113], v83 offset:0x1600
	ds_read_b64_tr_b16 v[114:115], v83 offset:0x1e00
	s_waitcnt lgkmcnt(8)
	v_add_f32_e32 v82, v82, v178
	v_mfma_f32_32x32x16_bf16 v[2:17], v[212:215], v[84:87], v[2:17]
	v_mfma_f32_32x32x16_bf16 v[50:65], v[212:215], v[88:91], v[50:65]
	v_mfma_f32_32x32x16_bf16 v[34:49], v[212:215], v[92:95], v[34:49]
	v_mfma_f32_32x32x16_bf16 v[18:33], v[212:215], v[96:99], v[18:33]
	ds_read_b64_tr_b16 v[78:79], v83 offset:0x2000
	ds_read_b64_tr_b16 v[80:81], v83 offset:0x2800
	ds_read_b64_tr_b16 v[84:85], v83 offset:0x2200
	ds_read_b64_tr_b16 v[86:87], v83 offset:0x2a00
	ds_read_b64_tr_b16 v[88:89], v83 offset:0x2400
	ds_read_b64_tr_b16 v[90:91], v83 offset:0x2c00
	ds_read_b64_tr_b16 v[92:93], v83 offset:0x2600
	ds_read_b64_tr_b16 v[94:95], v83 offset:0x2e00
	s_waitcnt lgkmcnt(8)
	v_mfma_f32_32x32x16_bf16 v[2:17], v[216:219], v[100:103], v[2:17]
	v_mfma_f32_32x32x16_bf16 v[50:65], v[216:219], v[104:107], v[50:65]
	v_mfma_f32_32x32x16_bf16 v[34:49], v[216:219], v[108:111], v[34:49]
	v_mfma_f32_32x32x16_bf16 v[18:33], v[216:219], v[112:115], v[18:33]
	ds_read_b64_tr_b16 v[74:75], v83 offset:0x3000
	ds_read_b64_tr_b16 v[76:77], v83 offset:0x3800
	ds_read_b64_tr_b16 v[96:97], v83 offset:0x3200
	ds_read_b64_tr_b16 v[98:99], v83 offset:0x3a00
	ds_read_b64_tr_b16 v[100:101], v83 offset:0x3400
	ds_read_b64_tr_b16 v[102:103], v83 offset:0x3c00
	ds_read_b64_tr_b16 v[104:105], v83 offset:0x3600
	ds_read_b64_tr_b16 v[106:107], v83 offset:0x3e00
	s_waitcnt lgkmcnt(8)
	v_mfma_f32_32x32x16_bf16 v[2:17], v[220:223], v[78:81], v[2:17]
	s_waitcnt lgkmcnt(0)
	v_mfma_f32_32x32x16_bf16 v[50:65], v[220:223], v[84:87], v[50:65]
	v_mfma_f32_32x32x16_bf16 v[34:49], v[220:223], v[88:91], v[34:49]
	v_mfma_f32_32x32x16_bf16 v[18:33], v[220:223], v[92:95], v[18:33]
	v_mfma_f32_32x32x16_bf16 v[2:17], v[224:227], v[74:77], v[2:17]
	s_waitcnt vmcnt(0)
	s_add_i32 s35, s35, 64
	s_add_u32 s89, s89, 0x170000
	s_addc_u32 s90, s90, 0
	s_cmp_eq_u32 s22, s17
	s_waitcnt vmcnt(0) lgkmcnt(0)
	s_barrier
	v_mfma_f32_32x32x16_bf16 v[50:65], v[224:227], v[96:99], v[50:65]
	v_mfma_f32_32x32x16_bf16 v[34:49], v[224:227], v[100:103], v[34:49]
	v_mfma_f32_32x32x16_bf16 v[18:33], v[224:227], v[104:107], v[18:33]
	s_cbranch_scc1 .LBB0_754
	v_mov_b32_e32 v178, v82
	s_branch .LBB0_740
